# GEMM main loops: per-cluster s_setprio flips removed, one static priority raise for waves 4-7 of every workgroup
# baseline (speedup 1.0000x reference)
_Z14fwd_megakernel3Ctx:
	s_load_dwordx8 s[4:11], s[0:1], 0x80
	s_mov_b32 s54, s2
	s_load_dword s2, s[0:1], 0xa8
	s_load_dwordx2 s[86:87], s[0:1], 0xa0
	v_and_b32_e32 v176, 0x3ff, v0
	v_readfirstlane_b32 s90, v176
	s_nop 3
	s_lshr_b32 s90, s90, 6
	s_cmp_ge_u32 s90, 4
	s_cbranch_scc0 .Lprio_done
	s_setprio 1
.Lprio_done:
	s_waitcnt lgkmcnt(0)
	v_writelane_b32 v252, s4, 0
	s_nop 1
	v_writelane_b32 v252, s5, 1
	v_writelane_b32 v252, s6, 2
	v_writelane_b32 v252, s7, 3
	v_writelane_b32 v252, s8, 4
	v_writelane_b32 v252, s9, 5
	v_writelane_b32 v252, s10, 6
	v_writelane_b32 v252, s11, 7
	s_add_u32 s6, s0, 0xa0
	s_addc_u32 s7, s1, 0
	v_writelane_b32 v252, s2, 8
	v_cmp_eq_u32_e64 s[2:3], 0, v176
	s_mov_b64 s[4:5], exec
	s_nop 0
	v_writelane_b32 v252, s2, 9
	s_nop 1
	v_writelane_b32 v252, s3, 10
	s_and_b64 s[2:3], s[4:5], s[2:3]
	s_mov_b64 exec, s[2:3]
	s_cbranch_execz .LBB0_2
	s_add_i32 s2, 0, 0x23fe0
	v_mov_b32_e32 v1, 0
	v_mov_b32_e32 v2, s2
	s_add_i32 s2, 0, 0x23fe4
	ds_write_b32 v2, v1
	v_mov_b32_e32 v2, s2
	ds_write_b32 v2, v1

.LBB0_175:
	ds_read_b128 v[150:153], v163
	ds_read_b128 v[154:157], v163 offset:1024
	ds_read_b128 v[168:171], v163 offset:2048
	ds_read_b128 v[172:175], v163 offset:3072
	ds_read_b128 v[178:181], v164
	ds_read_b128 v[182:185], v164 offset:1024
	ds_read_b128 v[186:189], v164 offset:2048
	ds_read_b128 v[190:193], v164 offset:3072
	s_add_u32 s26, s24, 0xfffc0080
	s_addc_u32 s27, s25, -1
	s_cmp_eq_u32 s50, 12
	s_cselect_b32 s29, s2, s27
	s_cselect_b32 s28, s7, s26
	s_cselect_b32 s27, s9, s33
	s_cselect_b32 s26, s17, s19
	v_lshl_add_u64 v[158:159], s[24:25], 0, v[142:143]
	s_add_i32 m0, s30, 0xc000
	ds_read_b128 v[194:197], v165
	ds_read_b128 v[198:201], v165 offset:1024
	ds_read_b128 v[202:205], v165 offset:2048
	ds_read_b128 v[206:209], v165 offset:3072
	ds_read_b128 v[210:213], v165 offset:4096
	ds_read_b128 v[214:217], v165 offset:5120
	ds_read_b128 v[218:221], v165 offset:6144
	ds_read_b128 v[222:225], v165 offset:7168
	global_load_lds_dwordx4 v[158:159], off
	v_lshl_add_u64 v[158:159], s[24:25], 0, v[144:145]
	s_add_i32 m0, s30, 0xe000
	s_nop 0
	global_load_lds_dwordx4 v[158:159], off
	s_waitcnt vmcnt(8)
	s_waitcnt lgkmcnt(0)
	s_barrier
	s_waitcnt lgkmcnt(0)
	v_mfma_f32_16x16x32_bf16 v[124:127], v[150:153], v[194:197], v[124:127]
	v_mfma_f32_16x16x32_bf16 v[120:123], v[168:171], v[194:197], v[120:123]
	v_mfma_f32_16x16x32_bf16 v[108:111], v[150:153], v[202:205], v[108:111]
	v_mfma_f32_16x16x32_bf16 v[104:107], v[168:171], v[202:205], v[104:107]
	v_mfma_f32_16x16x32_bf16 v[92:95], v[150:153], v[210:213], v[92:95]
	v_mfma_f32_16x16x32_bf16 v[88:91], v[168:171], v[210:213], v[88:91]
	v_mfma_f32_16x16x32_bf16 v[76:79], v[150:153], v[218:221], v[76:79]
	v_mfma_f32_16x16x32_bf16 v[72:75], v[168:171], v[218:221], v[72:75]
	v_mfma_f32_16x16x32_bf16 v[124:127], v[154:157], v[198:201], v[124:127]
	v_mfma_f32_16x16x32_bf16 v[120:123], v[172:175], v[198:201], v[120:123]
	v_mfma_f32_16x16x32_bf16 v[108:111], v[154:157], v[206:209], v[108:111]
	v_mfma_f32_16x16x32_bf16 v[104:107], v[172:175], v[206:209], v[104:107]
	v_mfma_f32_16x16x32_bf16 v[92:95], v[154:157], v[214:217], v[92:95]
	v_mfma_f32_16x16x32_bf16 v[88:91], v[172:175], v[214:217], v[88:91]
	v_mfma_f32_16x16x32_bf16 v[76:79], v[154:157], v[222:225], v[76:79]
	v_mfma_f32_16x16x32_bf16 v[72:75], v[172:175], v[222:225], v[72:75]
	v_mfma_f32_16x16x32_bf16 v[116:119], v[178:181], v[194:197], v[116:119]
	v_mfma_f32_16x16x32_bf16 v[112:115], v[186:189], v[194:197], v[112:115]
	v_mfma_f32_16x16x32_bf16 v[100:103], v[178:181], v[202:205], v[100:103]
	v_mfma_f32_16x16x32_bf16 v[96:99], v[186:189], v[202:205], v[96:99]
	v_mfma_f32_16x16x32_bf16 v[84:87], v[178:181], v[210:213], v[84:87]
	v_mfma_f32_16x16x32_bf16 v[80:83], v[186:189], v[210:213], v[80:83]
	v_mfma_f32_16x16x32_bf16 v[68:71], v[178:181], v[218:221], v[68:71]
	v_mfma_f32_16x16x32_bf16 v[64:67], v[186:189], v[218:221], v[64:67]
	v_mfma_f32_16x16x32_bf16 v[116:119], v[182:185], v[198:201], v[116:119]
	v_mfma_f32_16x16x32_bf16 v[112:115], v[190:193], v[198:201], v[112:115]
	v_mfma_f32_16x16x32_bf16 v[100:103], v[182:185], v[206:209], v[100:103]
	v_mfma_f32_16x16x32_bf16 v[96:99], v[190:193], v[206:209], v[96:99]
	v_mfma_f32_16x16x32_bf16 v[84:87], v[182:185], v[214:217], v[84:87]
	v_mfma_f32_16x16x32_bf16 v[80:83], v[190:193], v[214:217], v[80:83]
	v_mfma_f32_16x16x32_bf16 v[68:71], v[182:185], v[222:225], v[68:71]
	v_mfma_f32_16x16x32_bf16 v[64:67], v[190:193], v[222:225], v[64:67]
	s_barrier
	s_add_i32 s51, s45, s3
	v_lshl_add_u64 v[158:159], s[26:27], 0, v[130:131]
	s_mov_b32 m0, s51
	ds_read_b128 v[194:197], v165 offset:16384
	ds_read_b128 v[198:201], v165 offset:17408
	ds_read_b128 v[202:205], v165 offset:18432
	ds_read_b128 v[206:209], v165 offset:19456
	ds_read_b128 v[210:213], v165 offset:20480
	ds_read_b128 v[214:217], v165 offset:21504
	ds_read_b128 v[218:221], v165 offset:22528
	ds_read_b128 v[222:225], v165 offset:23552
	global_load_lds_dwordx4 v[158:159], off
	s_add_i32 m0, s51, 0x2000
	s_add_u32 s52, s26, 0x40000
	v_lshl_add_u64 v[226:227], s[26:27], 0, v[134:135]
	s_addc_u32 s53, s27, 0
	s_add_i32 s51, s46, s3
	global_load_lds_dwordx4 v[226:227], off
	v_lshl_add_u64 v[228:229], s[52:53], 0, v[130:131]
	s_mov_b32 m0, s51
	v_lshl_add_u64 v[230:231], s[28:29], 0, v[132:133]
	global_load_lds_dwordx4 v[228:229], off
	v_lshl_add_u64 v[228:229], s[52:53], 0, v[134:135]
	s_add_i32 m0, s51, 0x2000
	s_nop 0
	global_load_lds_dwordx4 v[228:229], off
	v_lshl_add_u64 v[228:229], s[28:29], 0, v[128:129]
	s_mov_b32 m0, s30
	s_nop 0
	global_load_lds_dwordx4 v[228:229], off
	s_mov_b32 m0, s31
	s_nop 0
	global_load_lds_dwordx4 v[230:231], off
	s_waitcnt vmcnt(8)
	s_waitcnt lgkmcnt(0)
	s_barrier
	s_waitcnt lgkmcnt(0)
	v_mfma_f32_16x16x32_bf16 v[60:63], v[150:153], v[194:197], v[60:63]
	v_mfma_f32_16x16x32_bf16 v[56:59], v[168:171], v[194:197], v[56:59]
	v_mfma_f32_16x16x32_bf16 v[44:47], v[150:153], v[202:205], v[44:47]
	v_mfma_f32_16x16x32_bf16 v[40:43], v[168:171], v[202:205], v[40:43]
	v_mfma_f32_16x16x32_bf16 v[28:31], v[150:153], v[210:213], v[28:31]
	v_mfma_f32_16x16x32_bf16 v[24:27], v[168:171], v[210:213], v[24:27]
	v_mfma_f32_16x16x32_bf16 v[12:15], v[150:153], v[218:221], v[12:15]
	v_mfma_f32_16x16x32_bf16 v[8:11], v[168:171], v[218:221], v[8:11]
	v_mfma_f32_16x16x32_bf16 v[60:63], v[154:157], v[198:201], v[60:63]
	v_mfma_f32_16x16x32_bf16 v[56:59], v[172:175], v[198:201], v[56:59]
	v_mfma_f32_16x16x32_bf16 v[44:47], v[154:157], v[206:209], v[44:47]
	v_mfma_f32_16x16x32_bf16 v[40:43], v[172:175], v[206:209], v[40:43]
	v_mfma_f32_16x16x32_bf16 v[28:31], v[154:157], v[214:217], v[28:31]
	v_mfma_f32_16x16x32_bf16 v[24:27], v[172:175], v[214:217], v[24:27]
	v_mfma_f32_16x16x32_bf16 v[12:15], v[154:157], v[222:225], v[12:15]
	v_mfma_f32_16x16x32_bf16 v[8:11], v[172:175], v[222:225], v[8:11]
	v_mfma_f32_16x16x32_bf16 v[52:55], v[178:181], v[194:197], v[52:55]
	v_mfma_f32_16x16x32_bf16 v[48:51], v[186:189], v[194:197], v[48:51]
	v_mfma_f32_16x16x32_bf16 v[36:39], v[178:181], v[202:205], v[36:39]
	v_mfma_f32_16x16x32_bf16 v[32:35], v[186:189], v[202:205], v[32:35]
	v_mfma_f32_16x16x32_bf16 v[20:23], v[178:181], v[210:213], v[20:23]
	v_mfma_f32_16x16x32_bf16 v[16:19], v[186:189], v[210:213], v[16:19]
	v_mfma_f32_16x16x32_bf16 v[4:7], v[178:181], v[218:221], v[4:7]
	v_mfma_f32_16x16x32_bf16 v[0:3], v[186:189], v[218:221], v[0:3]
	v_mfma_f32_16x16x32_bf16 v[52:55], v[182:185], v[198:201], v[52:55]
	v_mfma_f32_16x16x32_bf16 v[48:51], v[190:193], v[198:201], v[48:51]
	v_mfma_f32_16x16x32_bf16 v[36:39], v[182:185], v[206:209], v[36:39]
	v_mfma_f32_16x16x32_bf16 v[32:35], v[190:193], v[206:209], v[32:35]
	v_mfma_f32_16x16x32_bf16 v[20:23], v[182:185], v[214:217], v[20:23]
	v_mfma_f32_16x16x32_bf16 v[16:19], v[190:193], v[214:217], v[16:19]
	v_mfma_f32_16x16x32_bf16 v[4:7], v[182:185], v[222:225], v[4:7]
	v_mfma_f32_16x16x32_bf16 v[0:3], v[190:193], v[222:225], v[0:3]
	s_barrier
	s_add_i32 s51, 0, 0x18000
	v_add_u32_e32 v136, s51, v161
	s_add_i32 s52, 0, 0x1c000
	ds_read_b128 v[150:153], v136
	ds_read_b128 v[154:157], v136 offset:1024
	ds_read_b128 v[168:171], v136 offset:2048
	ds_read_b128 v[172:175], v136 offset:3072
	v_add_u32_e32 v136, s52, v161
	ds_read_b128 v[178:181], v136
	ds_read_b128 v[182:185], v136 offset:1024
	ds_read_b128 v[186:189], v136 offset:2048
	ds_read_b128 v[190:193], v136 offset:3072
	s_add_u32 s28, s28, 0x40000
	s_addc_u32 s29, s29, 0
	s_mov_b32 m0, s34
	v_lshl_add_u64 v[232:233], s[28:29], 0, v[128:129]
	ds_read_b128 v[194:197], v165 offset:32768
	ds_read_b128 v[198:201], v165 offset:33792
	ds_read_b128 v[202:205], v165 offset:34816
	ds_read_b128 v[206:209], v165 offset:35840
	ds_read_b128 v[210:213], v165 offset:36864
	ds_read_b128 v[214:217], v165 offset:37888
	ds_read_b128 v[218:221], v165 offset:38912
	ds_read_b128 v[222:225], v165 offset:39936
	global_load_lds_dwordx4 v[232:233], off
	v_lshl_add_u64 v[232:233], s[28:29], 0, v[132:133]
	s_mov_b32 m0, s35
	s_nop 0
	global_load_lds_dwordx4 v[232:233], off
	s_waitcnt vmcnt(8)
	s_waitcnt lgkmcnt(0)
	s_barrier
	s_waitcnt lgkmcnt(0)
	v_mfma_f32_16x16x32_bf16 v[124:127], v[150:153], v[194:197], v[124:127]
	v_mfma_f32_16x16x32_bf16 v[120:123], v[168:171], v[194:197], v[120:123]
	v_mfma_f32_16x16x32_bf16 v[108:111], v[150:153], v[202:205], v[108:111]
	v_mfma_f32_16x16x32_bf16 v[104:107], v[168:171], v[202:205], v[104:107]
	v_mfma_f32_16x16x32_bf16 v[92:95], v[150:153], v[210:213], v[92:95]
	v_mfma_f32_16x16x32_bf16 v[88:91], v[168:171], v[210:213], v[88:91]
	v_mfma_f32_16x16x32_bf16 v[76:79], v[150:153], v[218:221], v[76:79]
	v_mfma_f32_16x16x32_bf16 v[72:75], v[168:171], v[218:221], v[72:75]
	v_mfma_f32_16x16x32_bf16 v[124:127], v[154:157], v[198:201], v[124:127]
	v_mfma_f32_16x16x32_bf16 v[120:123], v[172:175], v[198:201], v[120:123]
	v_mfma_f32_16x16x32_bf16 v[108:111], v[154:157], v[206:209], v[108:111]
	v_mfma_f32_16x16x32_bf16 v[104:107], v[172:175], v[206:209], v[104:107]
	v_mfma_f32_16x16x32_bf16 v[92:95], v[154:157], v[214:217], v[92:95]
	v_mfma_f32_16x16x32_bf16 v[88:91], v[172:175], v[214:217], v[88:91]
	v_mfma_f32_16x16x32_bf16 v[76:79], v[154:157], v[222:225], v[76:79]
	v_mfma_f32_16x16x32_bf16 v[72:75], v[172:175], v[222:225], v[72:75]
	v_mfma_f32_16x16x32_bf16 v[116:119], v[178:181], v[194:197], v[116:119]
	v_mfma_f32_16x16x32_bf16 v[112:115], v[186:189], v[194:197], v[112:115]
	v_mfma_f32_16x16x32_bf16 v[100:103], v[178:181], v[202:205], v[100:103]
	v_mfma_f32_16x16x32_bf16 v[96:99], v[186:189], v[202:205], v[96:99]
	v_mfma_f32_16x16x32_bf16 v[84:87], v[178:181], v[210:213], v[84:87]
	v_mfma_f32_16x16x32_bf16 v[80:83], v[186:189], v[210:213], v[80:83]
	v_mfma_f32_16x16x32_bf16 v[68:71], v[178:181], v[218:221], v[68:71]
	v_mfma_f32_16x16x32_bf16 v[64:67], v[186:189], v[218:221], v[64:67]
	v_mfma_f32_16x16x32_bf16 v[116:119], v[182:185], v[198:201], v[116:119]
	v_mfma_f32_16x16x32_bf16 v[112:115], v[190:193], v[198:201], v[112:115]
	v_mfma_f32_16x16x32_bf16 v[100:103], v[182:185], v[206:209], v[100:103]
	v_mfma_f32_16x16x32_bf16 v[96:99], v[190:193], v[206:209], v[96:99]
	v_mfma_f32_16x16x32_bf16 v[84:87], v[182:185], v[214:217], v[84:87]
	v_mfma_f32_16x16x32_bf16 v[80:83], v[190:193], v[214:217], v[80:83]
	v_mfma_f32_16x16x32_bf16 v[68:71], v[182:185], v[222:225], v[68:71]
	v_mfma_f32_16x16x32_bf16 v[64:67], v[190:193], v[222:225], v[64:67]
	s_barrier
	s_add_i32 s28, s51, s3
	v_lshl_add_u64 v[158:159], v[158:159], 0, s[10:11]
	s_mov_b32 m0, s28
	ds_read_b128 v[194:197], v165 offset:49152
	ds_read_b128 v[198:201], v165 offset:50176
	ds_read_b128 v[202:205], v165 offset:51200
	ds_read_b128 v[206:209], v165 offset:52224
	ds_read_b128 v[210:213], v165 offset:53248
	ds_read_b128 v[214:217], v165 offset:54272
	ds_read_b128 v[218:221], v165 offset:55296
	ds_read_b128 v[222:225], v165 offset:56320
	global_load_lds_dwordx4 v[158:159], off
	s_add_i32 m0, s28, 0x2000
	s_add_u32 s26, s26, 0x40080
	v_lshl_add_u64 v[158:159], v[226:227], 0, s[10:11]
	s_addc_u32 s27, s27, 0
	s_add_i32 s28, s52, s3
	global_load_lds_dwordx4 v[158:159], off
	v_lshl_add_u64 v[158:159], s[26:27], 0, v[130:131]
	s_mov_b32 m0, s28
	s_nop 0
	global_load_lds_dwordx4 v[158:159], off
	v_lshl_add_u64 v[158:159], s[26:27], 0, v[134:135]
	s_add_i32 m0, s28, 0x2000
	s_nop 0
	global_load_lds_dwordx4 v[158:159], off
	v_lshl_add_u64 v[158:159], v[228:229], 0, s[10:11]
	s_mov_b32 m0, s38
	s_nop 0
	global_load_lds_dwordx4 v[158:159], off
	v_lshl_add_u64 v[158:159], v[230:231], 0, s[10:11]
	s_mov_b32 m0, s39
	s_nop 0
	global_load_lds_dwordx4 v[158:159], off
	s_waitcnt vmcnt(8)
	s_waitcnt lgkmcnt(0)
	s_barrier
	s_waitcnt lgkmcnt(0)
	v_mfma_f32_16x16x32_bf16 v[60:63], v[150:153], v[194:197], v[60:63]
	v_mfma_f32_16x16x32_bf16 v[56:59], v[168:171], v[194:197], v[56:59]
	v_mfma_f32_16x16x32_bf16 v[44:47], v[150:153], v[202:205], v[44:47]
	v_mfma_f32_16x16x32_bf16 v[40:43], v[168:171], v[202:205], v[40:43]
	v_mfma_f32_16x16x32_bf16 v[28:31], v[150:153], v[210:213], v[28:31]
	v_mfma_f32_16x16x32_bf16 v[24:27], v[168:171], v[210:213], v[24:27]
	v_mfma_f32_16x16x32_bf16 v[12:15], v[150:153], v[218:221], v[12:15]
	v_mfma_f32_16x16x32_bf16 v[8:11], v[168:171], v[218:221], v[8:11]
	v_mfma_f32_16x16x32_bf16 v[60:63], v[154:157], v[198:201], v[60:63]
	v_mfma_f32_16x16x32_bf16 v[56:59], v[172:175], v[198:201], v[56:59]
	v_mfma_f32_16x16x32_bf16 v[44:47], v[154:157], v[206:209], v[44:47]
	v_mfma_f32_16x16x32_bf16 v[40:43], v[172:175], v[206:209], v[40:43]
	v_mfma_f32_16x16x32_bf16 v[28:31], v[154:157], v[214:217], v[28:31]
	v_mfma_f32_16x16x32_bf16 v[24:27], v[172:175], v[214:217], v[24:27]
	v_mfma_f32_16x16x32_bf16 v[12:15], v[154:157], v[222:225], v[12:15]
	v_mfma_f32_16x16x32_bf16 v[8:11], v[172:175], v[222:225], v[8:11]
	v_mfma_f32_16x16x32_bf16 v[52:55], v[178:181], v[194:197], v[52:55]
	v_mfma_f32_16x16x32_bf16 v[48:51], v[186:189], v[194:197], v[48:51]
	v_mfma_f32_16x16x32_bf16 v[36:39], v[178:181], v[202:205], v[36:39]
	v_mfma_f32_16x16x32_bf16 v[32:35], v[186:189], v[202:205], v[32:35]
	v_mfma_f32_16x16x32_bf16 v[20:23], v[178:181], v[210:213], v[20:23]
	v_mfma_f32_16x16x32_bf16 v[16:19], v[186:189], v[210:213], v[16:19]
	v_mfma_f32_16x16x32_bf16 v[4:7], v[178:181], v[218:221], v[4:7]
	v_mfma_f32_16x16x32_bf16 v[0:3], v[186:189], v[218:221], v[0:3]
	v_mfma_f32_16x16x32_bf16 v[52:55], v[182:185], v[198:201], v[52:55]
	v_mfma_f32_16x16x32_bf16 v[48:51], v[190:193], v[198:201], v[48:51]
	v_mfma_f32_16x16x32_bf16 v[36:39], v[182:185], v[206:209], v[36:39]
	v_mfma_f32_16x16x32_bf16 v[32:35], v[190:193], v[206:209], v[32:35]
	v_mfma_f32_16x16x32_bf16 v[20:23], v[182:185], v[214:217], v[20:23]
	v_mfma_f32_16x16x32_bf16 v[16:19], v[190:193], v[214:217], v[16:19]
	v_mfma_f32_16x16x32_bf16 v[4:7], v[182:185], v[222:225], v[4:7]
	v_mfma_f32_16x16x32_bf16 v[0:3], v[190:193], v[222:225], v[0:3]
	s_barrier
	s_add_i32 s50, s50, 2
	s_add_u32 s24, s24, 0x100
	s_addc_u32 s25, s25, 0
	s_add_u32 s19, s19, 0x100
	s_addc_u32 s33, s33, 0
	s_cmp_gt_u32 s50, 13
	s_cbranch_scc0 .LBB0_175
	s_and_b64 vcc, exec, s[12:13]
	s_cbranch_vccz .LBB0_178
	s_barrier

.LBB0_679:
	ds_read_b128 v[144:147], v151
	ds_read_b128 v[154:157], v151 offset:1024
	ds_read_b128 v[158:161], v151 offset:2048
	ds_read_b128 v[162:165], v151 offset:3072
	ds_read_b128 v[166:169], v152
	ds_read_b128 v[170:173], v152 offset:1024
	ds_read_b128 v[178:181], v152 offset:2048
	ds_read_b128 v[182:185], v152 offset:3072
	s_add_u32 s40, s38, 0xfffe0080
	s_addc_u32 s41, s39, -1
	s_cmp_eq_u32 s58, 4
	s_cselect_b32 s43, s17, s41
	s_cselect_b32 s42, s54, s40
	s_cselect_b32 s41, s15, s57
	s_cselect_b32 s40, s55, s56
	v_lshl_add_u64 v[174:175], s[38:39], 0, v[136:137]
	s_add_i32 m0, s33, 0xc000
	ds_read_b128 v[186:189], v153
	ds_read_b128 v[190:193], v153 offset:1024
	ds_read_b128 v[194:197], v153 offset:2048
	ds_read_b128 v[198:201], v153 offset:3072
	ds_read_b128 v[202:205], v153 offset:4096
	ds_read_b128 v[206:209], v153 offset:5120
	ds_read_b128 v[210:213], v153 offset:6144
	ds_read_b128 v[214:217], v153 offset:7168
	global_load_lds_dwordx4 v[174:175], off
	v_lshl_add_u64 v[174:175], s[38:39], 0, v[138:139]
	s_add_i32 m0, s33, 0xe000
	s_nop 0
	global_load_lds_dwordx4 v[174:175], off
	s_waitcnt vmcnt(8)
	s_waitcnt lgkmcnt(0)
	s_barrier
	s_waitcnt lgkmcnt(0)
	v_mfma_f32_16x16x32_bf16 v[124:127], v[144:147], v[186:189], v[124:127]
	v_mfma_f32_16x16x32_bf16 v[120:123], v[158:161], v[186:189], v[120:123]
	v_mfma_f32_16x16x32_bf16 v[108:111], v[144:147], v[194:197], v[108:111]
	v_mfma_f32_16x16x32_bf16 v[104:107], v[158:161], v[194:197], v[104:107]
	v_mfma_f32_16x16x32_bf16 v[92:95], v[144:147], v[202:205], v[92:95]
	v_mfma_f32_16x16x32_bf16 v[88:91], v[158:161], v[202:205], v[88:91]
	v_mfma_f32_16x16x32_bf16 v[76:79], v[144:147], v[210:213], v[76:79]
	v_mfma_f32_16x16x32_bf16 v[72:75], v[158:161], v[210:213], v[72:75]
	v_mfma_f32_16x16x32_bf16 v[124:127], v[154:157], v[190:193], v[124:127]
	v_mfma_f32_16x16x32_bf16 v[120:123], v[162:165], v[190:193], v[120:123]
	v_mfma_f32_16x16x32_bf16 v[108:111], v[154:157], v[198:201], v[108:111]
	v_mfma_f32_16x16x32_bf16 v[104:107], v[162:165], v[198:201], v[104:107]
	v_mfma_f32_16x16x32_bf16 v[92:95], v[154:157], v[206:209], v[92:95]
	v_mfma_f32_16x16x32_bf16 v[88:91], v[162:165], v[206:209], v[88:91]
	v_mfma_f32_16x16x32_bf16 v[76:79], v[154:157], v[214:217], v[76:79]
	v_mfma_f32_16x16x32_bf16 v[72:75], v[162:165], v[214:217], v[72:75]
	v_mfma_f32_16x16x32_bf16 v[116:119], v[166:169], v[186:189], v[116:119]
	v_mfma_f32_16x16x32_bf16 v[112:115], v[178:181], v[186:189], v[112:115]
	v_mfma_f32_16x16x32_bf16 v[100:103], v[166:169], v[194:197], v[100:103]
	v_mfma_f32_16x16x32_bf16 v[96:99], v[178:181], v[194:197], v[96:99]
	v_mfma_f32_16x16x32_bf16 v[84:87], v[166:169], v[202:205], v[84:87]
	v_mfma_f32_16x16x32_bf16 v[80:83], v[178:181], v[202:205], v[80:83]
	v_mfma_f32_16x16x32_bf16 v[68:71], v[166:169], v[210:213], v[68:71]
	v_mfma_f32_16x16x32_bf16 v[64:67], v[178:181], v[210:213], v[64:67]
	v_mfma_f32_16x16x32_bf16 v[116:119], v[170:173], v[190:193], v[116:119]
	v_mfma_f32_16x16x32_bf16 v[112:115], v[182:185], v[190:193], v[112:115]
	v_mfma_f32_16x16x32_bf16 v[100:103], v[170:173], v[198:201], v[100:103]
	v_mfma_f32_16x16x32_bf16 v[96:99], v[182:185], v[198:201], v[96:99]
	v_mfma_f32_16x16x32_bf16 v[84:87], v[170:173], v[206:209], v[84:87]
	v_mfma_f32_16x16x32_bf16 v[80:83], v[182:185], v[206:209], v[80:83]
	v_mfma_f32_16x16x32_bf16 v[68:71], v[170:173], v[214:217], v[68:71]
	v_mfma_f32_16x16x32_bf16 v[64:67], v[182:185], v[214:217], v[64:67]
	s_barrier
	s_add_i32 s59, s51, s3
	v_lshl_add_u64 v[174:175], s[40:41], 0, v[130:131]
	s_mov_b32 m0, s59
	ds_read_b128 v[186:189], v153 offset:16384
	ds_read_b128 v[190:193], v153 offset:17408
	ds_read_b128 v[194:197], v153 offset:18432
	ds_read_b128 v[198:201], v153 offset:19456
	ds_read_b128 v[202:205], v153 offset:20480
	ds_read_b128 v[206:209], v153 offset:21504
	ds_read_b128 v[210:213], v153 offset:22528
	ds_read_b128 v[214:217], v153 offset:23552
	global_load_lds_dwordx4 v[174:175], off
	s_add_i32 m0, s59, 0x2000
	s_add_u32 s60, s40, 0x20000
	v_lshl_add_u64 v[218:219], s[40:41], 0, v[134:135]
	s_addc_u32 s61, s41, 0
	s_add_i32 s59, s52, s3
	global_load_lds_dwordx4 v[218:219], off
	v_lshl_add_u64 v[220:221], s[60:61], 0, v[130:131]
	s_mov_b32 m0, s59
	v_lshl_add_u64 v[222:223], s[42:43], 0, v[132:133]
	global_load_lds_dwordx4 v[220:221], off
	v_lshl_add_u64 v[220:221], s[60:61], 0, v[134:135]
	s_add_i32 m0, s59, 0x2000
	s_nop 0
	global_load_lds_dwordx4 v[220:221], off
	v_lshl_add_u64 v[220:221], s[42:43], 0, v[128:129]
	s_mov_b32 m0, s33
	s_nop 0
	global_load_lds_dwordx4 v[220:221], off
	s_mov_b32 m0, s37
	s_nop 0
	global_load_lds_dwordx4 v[222:223], off
	s_waitcnt vmcnt(8)
	s_waitcnt lgkmcnt(0)
	s_barrier
	s_waitcnt lgkmcnt(0)
	v_mfma_f32_16x16x32_bf16 v[60:63], v[144:147], v[186:189], v[60:63]
	v_mfma_f32_16x16x32_bf16 v[56:59], v[158:161], v[186:189], v[56:59]
	v_mfma_f32_16x16x32_bf16 v[44:47], v[144:147], v[194:197], v[44:47]
	v_mfma_f32_16x16x32_bf16 v[40:43], v[158:161], v[194:197], v[40:43]
	v_mfma_f32_16x16x32_bf16 v[28:31], v[144:147], v[202:205], v[28:31]
	v_mfma_f32_16x16x32_bf16 v[24:27], v[158:161], v[202:205], v[24:27]
	v_mfma_f32_16x16x32_bf16 v[12:15], v[144:147], v[210:213], v[12:15]
	v_mfma_f32_16x16x32_bf16 v[8:11], v[158:161], v[210:213], v[8:11]
	v_mfma_f32_16x16x32_bf16 v[60:63], v[154:157], v[190:193], v[60:63]
	v_mfma_f32_16x16x32_bf16 v[56:59], v[162:165], v[190:193], v[56:59]
	v_mfma_f32_16x16x32_bf16 v[44:47], v[154:157], v[198:201], v[44:47]
	v_mfma_f32_16x16x32_bf16 v[40:43], v[162:165], v[198:201], v[40:43]
	v_mfma_f32_16x16x32_bf16 v[28:31], v[154:157], v[206:209], v[28:31]
	v_mfma_f32_16x16x32_bf16 v[24:27], v[162:165], v[206:209], v[24:27]
	v_mfma_f32_16x16x32_bf16 v[12:15], v[154:157], v[214:217], v[12:15]
	v_mfma_f32_16x16x32_bf16 v[8:11], v[162:165], v[214:217], v[8:11]
	v_mfma_f32_16x16x32_bf16 v[52:55], v[166:169], v[186:189], v[52:55]
	v_mfma_f32_16x16x32_bf16 v[48:51], v[178:181], v[186:189], v[48:51]
	v_mfma_f32_16x16x32_bf16 v[36:39], v[166:169], v[194:197], v[36:39]
	v_mfma_f32_16x16x32_bf16 v[32:35], v[178:181], v[194:197], v[32:35]
	v_mfma_f32_16x16x32_bf16 v[20:23], v[166:169], v[202:205], v[20:23]
	v_mfma_f32_16x16x32_bf16 v[16:19], v[178:181], v[202:205], v[16:19]
	v_mfma_f32_16x16x32_bf16 v[4:7], v[166:169], v[210:213], v[4:7]
	v_mfma_f32_16x16x32_bf16 v[0:3], v[178:181], v[210:213], v[0:3]
	v_mfma_f32_16x16x32_bf16 v[52:55], v[170:173], v[190:193], v[52:55]
	v_mfma_f32_16x16x32_bf16 v[48:51], v[182:185], v[190:193], v[48:51]
	v_mfma_f32_16x16x32_bf16 v[36:39], v[170:173], v[198:201], v[36:39]
	v_mfma_f32_16x16x32_bf16 v[32:35], v[182:185], v[198:201], v[32:35]
	v_mfma_f32_16x16x32_bf16 v[20:23], v[170:173], v[206:209], v[20:23]
	v_mfma_f32_16x16x32_bf16 v[16:19], v[182:185], v[206:209], v[16:19]
	v_mfma_f32_16x16x32_bf16 v[4:7], v[170:173], v[214:217], v[4:7]
	v_mfma_f32_16x16x32_bf16 v[0:3], v[182:185], v[214:217], v[0:3]
	s_barrier
	s_add_i32 s59, 0, 0x18000
	s_add_i32 s60, 0, 0x1c000
	v_add_u32_e32 v162, s59, v149
	v_add_u32_e32 v182, s60, v149
	ds_read_b128 v[144:147], v162
	ds_read_b128 v[154:157], v162 offset:1024
	ds_read_b128 v[158:161], v162 offset:2048
	ds_read_b128 v[162:165], v162 offset:3072
	ds_read_b128 v[166:169], v182
	ds_read_b128 v[170:173], v182 offset:1024
	ds_read_b128 v[178:181], v182 offset:2048
	ds_read_b128 v[182:185], v182 offset:3072
	s_add_u32 s42, s42, 0x20000
	s_addc_u32 s43, s43, 0
	s_mov_b32 m0, s44
	v_lshl_add_u64 v[224:225], s[42:43], 0, v[128:129]
	ds_read_b128 v[186:189], v153 offset:32768
	ds_read_b128 v[190:193], v153 offset:33792
	ds_read_b128 v[194:197], v153 offset:34816
	ds_read_b128 v[198:201], v153 offset:35840
	ds_read_b128 v[202:205], v153 offset:36864
	ds_read_b128 v[206:209], v153 offset:37888
	ds_read_b128 v[210:213], v153 offset:38912
	ds_read_b128 v[214:217], v153 offset:39936
	global_load_lds_dwordx4 v[224:225], off
	v_lshl_add_u64 v[224:225], s[42:43], 0, v[132:133]
	s_mov_b32 m0, s45
	s_nop 0
	global_load_lds_dwordx4 v[224:225], off
	s_waitcnt vmcnt(8)
	s_waitcnt lgkmcnt(0)
	s_barrier
	s_waitcnt lgkmcnt(0)
	v_mfma_f32_16x16x32_bf16 v[124:127], v[144:147], v[186:189], v[124:127]
	v_mfma_f32_16x16x32_bf16 v[120:123], v[158:161], v[186:189], v[120:123]
	v_mfma_f32_16x16x32_bf16 v[108:111], v[144:147], v[194:197], v[108:111]
	v_mfma_f32_16x16x32_bf16 v[104:107], v[158:161], v[194:197], v[104:107]
	v_mfma_f32_16x16x32_bf16 v[92:95], v[144:147], v[202:205], v[92:95]
	v_mfma_f32_16x16x32_bf16 v[88:91], v[158:161], v[202:205], v[88:91]
	v_mfma_f32_16x16x32_bf16 v[76:79], v[144:147], v[210:213], v[76:79]
	v_mfma_f32_16x16x32_bf16 v[72:75], v[158:161], v[210:213], v[72:75]
	v_mfma_f32_16x16x32_bf16 v[124:127], v[154:157], v[190:193], v[124:127]
	v_mfma_f32_16x16x32_bf16 v[120:123], v[162:165], v[190:193], v[120:123]
	v_mfma_f32_16x16x32_bf16 v[108:111], v[154:157], v[198:201], v[108:111]
	v_mfma_f32_16x16x32_bf16 v[104:107], v[162:165], v[198:201], v[104:107]
	v_mfma_f32_16x16x32_bf16 v[92:95], v[154:157], v[206:209], v[92:95]
	v_mfma_f32_16x16x32_bf16 v[88:91], v[162:165], v[206:209], v[88:91]
	v_mfma_f32_16x16x32_bf16 v[76:79], v[154:157], v[214:217], v[76:79]
	v_mfma_f32_16x16x32_bf16 v[72:75], v[162:165], v[214:217], v[72:75]
	v_mfma_f32_16x16x32_bf16 v[116:119], v[166:169], v[186:189], v[116:119]
	v_mfma_f32_16x16x32_bf16 v[112:115], v[178:181], v[186:189], v[112:115]
	v_mfma_f32_16x16x32_bf16 v[100:103], v[166:169], v[194:197], v[100:103]
	v_mfma_f32_16x16x32_bf16 v[96:99], v[178:181], v[194:197], v[96:99]
	v_mfma_f32_16x16x32_bf16 v[84:87], v[166:169], v[202:205], v[84:87]
	v_mfma_f32_16x16x32_bf16 v[80:83], v[178:181], v[202:205], v[80:83]
	v_mfma_f32_16x16x32_bf16 v[68:71], v[166:169], v[210:213], v[68:71]
	v_mfma_f32_16x16x32_bf16 v[64:67], v[178:181], v[210:213], v[64:67]
	v_mfma_f32_16x16x32_bf16 v[116:119], v[170:173], v[190:193], v[116:119]
	v_mfma_f32_16x16x32_bf16 v[112:115], v[182:185], v[190:193], v[112:115]
	v_mfma_f32_16x16x32_bf16 v[100:103], v[170:173], v[198:201], v[100:103]
	v_mfma_f32_16x16x32_bf16 v[96:99], v[182:185], v[198:201], v[96:99]
	v_mfma_f32_16x16x32_bf16 v[84:87], v[170:173], v[206:209], v[84:87]
	v_mfma_f32_16x16x32_bf16 v[80:83], v[182:185], v[206:209], v[80:83]
	v_mfma_f32_16x16x32_bf16 v[68:71], v[170:173], v[214:217], v[68:71]
	v_mfma_f32_16x16x32_bf16 v[64:67], v[182:185], v[214:217], v[64:67]
	s_barrier
	s_add_i32 s42, s59, s3
	v_lshl_add_u64 v[174:175], v[174:175], 0, s[8:9]
	s_mov_b32 m0, s42
	ds_read_b128 v[186:189], v153 offset:49152
	ds_read_b128 v[190:193], v153 offset:50176
	ds_read_b128 v[194:197], v153 offset:51200
	ds_read_b128 v[198:201], v153 offset:52224
	ds_read_b128 v[202:205], v153 offset:53248
	ds_read_b128 v[206:209], v153 offset:54272
	ds_read_b128 v[210:213], v153 offset:55296
	ds_read_b128 v[214:217], v153 offset:56320
	global_load_lds_dwordx4 v[174:175], off
	s_add_i32 m0, s42, 0x2000
	s_add_u32 s40, s40, 0x20080
	v_lshl_add_u64 v[174:175], v[218:219], 0, s[8:9]
	s_addc_u32 s41, s41, 0
	s_add_i32 s42, s60, s3
	global_load_lds_dwordx4 v[174:175], off
	v_lshl_add_u64 v[174:175], s[40:41], 0, v[130:131]
	s_mov_b32 m0, s42
	s_nop 0
	global_load_lds_dwordx4 v[174:175], off
	v_lshl_add_u64 v[174:175], s[40:41], 0, v[134:135]
	s_add_i32 m0, s42, 0x2000
	s_nop 0
	global_load_lds_dwordx4 v[174:175], off
	v_lshl_add_u64 v[174:175], v[220:221], 0, s[8:9]
	s_mov_b32 m0, s47
	s_nop 0
	global_load_lds_dwordx4 v[174:175], off
	v_lshl_add_u64 v[174:175], v[222:223], 0, s[8:9]
	s_mov_b32 m0, s48
	s_nop 0
	global_load_lds_dwordx4 v[174:175], off
	s_waitcnt vmcnt(8)
	s_waitcnt lgkmcnt(0)
	s_barrier
	s_waitcnt lgkmcnt(0)
	v_mfma_f32_16x16x32_bf16 v[60:63], v[144:147], v[186:189], v[60:63]
	v_mfma_f32_16x16x32_bf16 v[56:59], v[158:161], v[186:189], v[56:59]
	v_mfma_f32_16x16x32_bf16 v[44:47], v[144:147], v[194:197], v[44:47]
	v_mfma_f32_16x16x32_bf16 v[40:43], v[158:161], v[194:197], v[40:43]
	v_mfma_f32_16x16x32_bf16 v[28:31], v[144:147], v[202:205], v[28:31]
	v_mfma_f32_16x16x32_bf16 v[24:27], v[158:161], v[202:205], v[24:27]
	v_mfma_f32_16x16x32_bf16 v[12:15], v[144:147], v[210:213], v[12:15]
	v_mfma_f32_16x16x32_bf16 v[8:11], v[158:161], v[210:213], v[8:11]
	v_mfma_f32_16x16x32_bf16 v[60:63], v[154:157], v[190:193], v[60:63]
	v_mfma_f32_16x16x32_bf16 v[56:59], v[162:165], v[190:193], v[56:59]
	v_mfma_f32_16x16x32_bf16 v[44:47], v[154:157], v[198:201], v[44:47]
	v_mfma_f32_16x16x32_bf16 v[40:43], v[162:165], v[198:201], v[40:43]
	v_mfma_f32_16x16x32_bf16 v[28:31], v[154:157], v[206:209], v[28:31]
	v_mfma_f32_16x16x32_bf16 v[24:27], v[162:165], v[206:209], v[24:27]
	v_mfma_f32_16x16x32_bf16 v[12:15], v[154:157], v[214:217], v[12:15]
	v_mfma_f32_16x16x32_bf16 v[8:11], v[162:165], v[214:217], v[8:11]
	v_mfma_f32_16x16x32_bf16 v[52:55], v[166:169], v[186:189], v[52:55]
	v_mfma_f32_16x16x32_bf16 v[48:51], v[178:181], v[186:189], v[48:51]
	v_mfma_f32_16x16x32_bf16 v[36:39], v[166:169], v[194:197], v[36:39]
	v_mfma_f32_16x16x32_bf16 v[32:35], v[178:181], v[194:197], v[32:35]
	v_mfma_f32_16x16x32_bf16 v[20:23], v[166:169], v[202:205], v[20:23]
	v_mfma_f32_16x16x32_bf16 v[16:19], v[178:181], v[202:205], v[16:19]
	v_mfma_f32_16x16x32_bf16 v[4:7], v[166:169], v[210:213], v[4:7]
	v_mfma_f32_16x16x32_bf16 v[0:3], v[178:181], v[210:213], v[0:3]
	v_mfma_f32_16x16x32_bf16 v[52:55], v[170:173], v[190:193], v[52:55]
	v_mfma_f32_16x16x32_bf16 v[48:51], v[182:185], v[190:193], v[48:51]
	v_mfma_f32_16x16x32_bf16 v[36:39], v[170:173], v[198:201], v[36:39]
	v_mfma_f32_16x16x32_bf16 v[32:35], v[182:185], v[198:201], v[32:35]
	v_mfma_f32_16x16x32_bf16 v[20:23], v[170:173], v[206:209], v[20:23]
	v_mfma_f32_16x16x32_bf16 v[16:19], v[182:185], v[206:209], v[16:19]
	v_mfma_f32_16x16x32_bf16 v[4:7], v[170:173], v[214:217], v[4:7]
	v_mfma_f32_16x16x32_bf16 v[0:3], v[182:185], v[214:217], v[0:3]
	s_barrier
	s_add_i32 s58, s58, 2
	s_add_u32 s38, s38, 0x100
	s_addc_u32 s39, s39, 0
	s_add_u32 s56, s56, 0x100
	s_addc_u32 s57, s57, 0
	s_cmp_gt_u32 s58, 5
	s_cbranch_scc0 .LBB0_679
	s_and_b64 vcc, exec, s[10:11]
	s_cbranch_vccz .LBB0_682
	s_barrier

.LBB0_710:
	v_add_u32_e32 v1, s49, v149
	ds_read_b128 v[150:153], v1
	ds_read_b128 v[162:165], v1 offset:1024
	ds_read_b128 v[166:169], v1 offset:2048
	ds_read_b128 v[170:173], v1 offset:3072
	v_add_u32_e32 v1, s50, v149
	ds_read_b128 v[178:181], v1
	ds_read_b128 v[182:185], v1 offset:1024
	ds_read_b128 v[186:189], v1 offset:2048
	ds_read_b128 v[190:193], v1 offset:3072
	s_add_u32 s38, s36, 0xfffc0080
	s_addc_u32 s39, s37, -1
	s_cmp_eq_u32 s66, 0
	s_cselect_b32 s41, s27, s39
	s_cselect_b32 s40, s62, s38
	s_cselect_b32 s39, s17, s65
	s_cselect_b32 s38, s63, s64
	v_lshl_add_u64 v[174:175], s[36:37], 0, v[138:139]
	s_add_i32 m0, s35, 0xc000
	ds_read_b128 v[194:197], v161
	ds_read_b128 v[198:201], v161 offset:1024
	ds_read_b128 v[202:205], v161 offset:2048
	ds_read_b128 v[206:209], v161 offset:3072
	ds_read_b128 v[210:213], v161 offset:4096
	ds_read_b128 v[214:217], v161 offset:5120
	ds_read_b128 v[218:221], v161 offset:6144
	ds_read_b128 v[222:225], v161 offset:7168
	global_load_lds_dwordx4 v[174:175], off
	v_lshl_add_u64 v[174:175], s[36:37], 0, v[140:141]
	s_add_i32 m0, s35, 0xe000
	s_nop 0
	global_load_lds_dwordx4 v[174:175], off
	s_waitcnt vmcnt(8)
	s_waitcnt lgkmcnt(0)
	s_barrier
	s_waitcnt lgkmcnt(0)
	v_mfma_f32_16x16x32_bf16 v[126:129], v[150:153], v[194:197], v[126:129]
	v_mfma_f32_16x16x32_bf16 v[122:125], v[166:169], v[194:197], v[122:125]
	v_mfma_f32_16x16x32_bf16 v[110:113], v[150:153], v[202:205], v[110:113]
	v_mfma_f32_16x16x32_bf16 v[106:109], v[166:169], v[202:205], v[106:109]
	v_mfma_f32_16x16x32_bf16 v[94:97], v[150:153], v[210:213], v[94:97]
	v_mfma_f32_16x16x32_bf16 v[90:93], v[166:169], v[210:213], v[90:93]
	v_mfma_f32_16x16x32_bf16 v[78:81], v[150:153], v[218:221], v[78:81]
	v_mfma_f32_16x16x32_bf16 v[74:77], v[166:169], v[218:221], v[74:77]
	v_mfma_f32_16x16x32_bf16 v[126:129], v[162:165], v[198:201], v[126:129]
	v_mfma_f32_16x16x32_bf16 v[122:125], v[170:173], v[198:201], v[122:125]
	v_mfma_f32_16x16x32_bf16 v[110:113], v[162:165], v[206:209], v[110:113]
	v_mfma_f32_16x16x32_bf16 v[106:109], v[170:173], v[206:209], v[106:109]
	v_mfma_f32_16x16x32_bf16 v[94:97], v[162:165], v[214:217], v[94:97]
	v_mfma_f32_16x16x32_bf16 v[90:93], v[170:173], v[214:217], v[90:93]
	v_mfma_f32_16x16x32_bf16 v[78:81], v[162:165], v[222:225], v[78:81]
	v_mfma_f32_16x16x32_bf16 v[74:77], v[170:173], v[222:225], v[74:77]
	v_mfma_f32_16x16x32_bf16 v[118:121], v[178:181], v[194:197], v[118:121]
	v_mfma_f32_16x16x32_bf16 v[114:117], v[186:189], v[194:197], v[114:117]
	v_mfma_f32_16x16x32_bf16 v[102:105], v[178:181], v[202:205], v[102:105]
	v_mfma_f32_16x16x32_bf16 v[98:101], v[186:189], v[202:205], v[98:101]
	v_mfma_f32_16x16x32_bf16 v[86:89], v[178:181], v[210:213], v[86:89]
	v_mfma_f32_16x16x32_bf16 v[82:85], v[186:189], v[210:213], v[82:85]
	v_mfma_f32_16x16x32_bf16 v[70:73], v[178:181], v[218:221], v[70:73]
	v_mfma_f32_16x16x32_bf16 v[66:69], v[186:189], v[218:221], v[66:69]
	v_mfma_f32_16x16x32_bf16 v[118:121], v[182:185], v[198:201], v[118:121]
	v_mfma_f32_16x16x32_bf16 v[114:117], v[190:193], v[198:201], v[114:117]
	v_mfma_f32_16x16x32_bf16 v[102:105], v[182:185], v[206:209], v[102:105]
	v_mfma_f32_16x16x32_bf16 v[98:101], v[190:193], v[206:209], v[98:101]
	v_mfma_f32_16x16x32_bf16 v[86:89], v[182:185], v[214:217], v[86:89]
	v_mfma_f32_16x16x32_bf16 v[82:85], v[190:193], v[214:217], v[82:85]
	v_mfma_f32_16x16x32_bf16 v[70:73], v[182:185], v[222:225], v[70:73]
	v_mfma_f32_16x16x32_bf16 v[66:69], v[190:193], v[222:225], v[66:69]
	s_barrier
	s_add_i32 s68, s49, s42
	v_lshl_add_u64 v[174:175], s[38:39], 0, v[132:133]
	s_mov_b32 m0, s68
	ds_read_b128 v[194:197], v161 offset:16384
	ds_read_b128 v[198:201], v161 offset:17408
	ds_read_b128 v[202:205], v161 offset:18432
	ds_read_b128 v[206:209], v161 offset:19456
	ds_read_b128 v[210:213], v161 offset:20480
	ds_read_b128 v[214:217], v161 offset:21504
	ds_read_b128 v[218:221], v161 offset:22528
	ds_read_b128 v[222:225], v161 offset:23552
	global_load_lds_dwordx4 v[174:175], off
	s_add_i32 m0, s68, 0x2000
	s_add_u32 s68, s38, 0x40000
	v_lshl_add_u64 v[226:227], s[38:39], 0, v[136:137]
	s_addc_u32 s69, s39, 0
	s_add_i32 s70, s50, s42
	global_load_lds_dwordx4 v[226:227], off
	v_lshl_add_u64 v[228:229], s[68:69], 0, v[132:133]
	s_mov_b32 m0, s70
	v_lshl_add_u64 v[230:231], s[40:41], 0, v[134:135]
	global_load_lds_dwordx4 v[228:229], off
	v_lshl_add_u64 v[228:229], s[68:69], 0, v[136:137]
	s_add_i32 m0, s70, 0x2000
	s_nop 0
	global_load_lds_dwordx4 v[228:229], off
	v_lshl_add_u64 v[228:229], s[40:41], 0, v[130:131]
	s_mov_b32 m0, s35
	s_nop 0
	global_load_lds_dwordx4 v[228:229], off
	s_mov_b32 m0, s43
	s_nop 0
	global_load_lds_dwordx4 v[230:231], off
	s_waitcnt vmcnt(8)
	s_waitcnt lgkmcnt(0)
	s_barrier
	s_waitcnt lgkmcnt(0)
	v_mfma_f32_16x16x32_bf16 v[62:65], v[150:153], v[194:197], v[62:65]
	v_mfma_f32_16x16x32_bf16 v[58:61], v[166:169], v[194:197], v[58:61]
	v_mfma_f32_16x16x32_bf16 v[46:49], v[150:153], v[202:205], v[46:49]
	v_mfma_f32_16x16x32_bf16 v[42:45], v[166:169], v[202:205], v[42:45]
	v_mfma_f32_16x16x32_bf16 v[30:33], v[150:153], v[210:213], v[30:33]
	v_mfma_f32_16x16x32_bf16 v[26:29], v[166:169], v[210:213], v[26:29]
	v_mfma_f32_16x16x32_bf16 v[14:17], v[150:153], v[218:221], v[14:17]
	v_mfma_f32_16x16x32_bf16 v[10:13], v[166:169], v[218:221], v[10:13]
	v_mfma_f32_16x16x32_bf16 v[62:65], v[162:165], v[198:201], v[62:65]
	v_mfma_f32_16x16x32_bf16 v[58:61], v[170:173], v[198:201], v[58:61]
	v_mfma_f32_16x16x32_bf16 v[46:49], v[162:165], v[206:209], v[46:49]
	v_mfma_f32_16x16x32_bf16 v[42:45], v[170:173], v[206:209], v[42:45]
	v_mfma_f32_16x16x32_bf16 v[30:33], v[162:165], v[214:217], v[30:33]
	v_mfma_f32_16x16x32_bf16 v[26:29], v[170:173], v[214:217], v[26:29]
	v_mfma_f32_16x16x32_bf16 v[14:17], v[162:165], v[222:225], v[14:17]
	v_mfma_f32_16x16x32_bf16 v[10:13], v[170:173], v[222:225], v[10:13]
	v_mfma_f32_16x16x32_bf16 v[54:57], v[178:181], v[194:197], v[54:57]
	v_mfma_f32_16x16x32_bf16 v[50:53], v[186:189], v[194:197], v[50:53]
	v_mfma_f32_16x16x32_bf16 v[38:41], v[178:181], v[202:205], v[38:41]
	v_mfma_f32_16x16x32_bf16 v[34:37], v[186:189], v[202:205], v[34:37]
	v_mfma_f32_16x16x32_bf16 v[22:25], v[178:181], v[210:213], v[22:25]
	v_mfma_f32_16x16x32_bf16 v[18:21], v[186:189], v[210:213], v[18:21]
	v_mfma_f32_16x16x32_bf16 v[6:9], v[178:181], v[218:221], v[6:9]
	v_mfma_f32_16x16x32_bf16 v[2:5], v[186:189], v[218:221], v[2:5]
	v_mfma_f32_16x16x32_bf16 v[54:57], v[182:185], v[198:201], v[54:57]
	v_mfma_f32_16x16x32_bf16 v[50:53], v[190:193], v[198:201], v[50:53]
	v_mfma_f32_16x16x32_bf16 v[38:41], v[182:185], v[206:209], v[38:41]
	v_mfma_f32_16x16x32_bf16 v[34:37], v[190:193], v[206:209], v[34:37]
	v_mfma_f32_16x16x32_bf16 v[22:25], v[182:185], v[214:217], v[22:25]
	v_mfma_f32_16x16x32_bf16 v[18:21], v[190:193], v[214:217], v[18:21]
	v_mfma_f32_16x16x32_bf16 v[6:9], v[182:185], v[222:225], v[6:9]
	v_mfma_f32_16x16x32_bf16 v[2:5], v[190:193], v[222:225], v[2:5]
	s_barrier
	v_add_u32_e32 v1, s51, v149
	ds_read_b128 v[150:153], v1
	ds_read_b128 v[162:165], v1 offset:1024
	ds_read_b128 v[166:169], v1 offset:2048
	ds_read_b128 v[170:173], v1 offset:3072
	v_add_u32_e32 v1, s52, v149
	ds_read_b128 v[178:181], v1
	ds_read_b128 v[182:185], v1 offset:1024
	ds_read_b128 v[186:189], v1 offset:2048
	ds_read_b128 v[190:193], v1 offset:3072
	s_add_u32 s40, s40, 0x40000
	s_addc_u32 s41, s41, 0
	s_mov_b32 m0, s44
	v_lshl_add_u64 v[232:233], s[40:41], 0, v[130:131]
	ds_read_b128 v[194:197], v161 offset:32768
	ds_read_b128 v[198:201], v161 offset:33792
	ds_read_b128 v[202:205], v161 offset:34816
	ds_read_b128 v[206:209], v161 offset:35840
	ds_read_b128 v[210:213], v161 offset:36864
	ds_read_b128 v[214:217], v161 offset:37888
	ds_read_b128 v[218:221], v161 offset:38912
	ds_read_b128 v[222:225], v161 offset:39936
	global_load_lds_dwordx4 v[232:233], off
	v_lshl_add_u64 v[232:233], s[40:41], 0, v[134:135]
	s_mov_b32 m0, s45
	s_nop 0
	global_load_lds_dwordx4 v[232:233], off
	s_waitcnt vmcnt(8)
	s_waitcnt lgkmcnt(0)
	s_barrier
	s_waitcnt lgkmcnt(0)
	v_mfma_f32_16x16x32_bf16 v[126:129], v[150:153], v[194:197], v[126:129]
	v_mfma_f32_16x16x32_bf16 v[122:125], v[166:169], v[194:197], v[122:125]
	v_mfma_f32_16x16x32_bf16 v[110:113], v[150:153], v[202:205], v[110:113]
	v_mfma_f32_16x16x32_bf16 v[106:109], v[166:169], v[202:205], v[106:109]
	v_mfma_f32_16x16x32_bf16 v[94:97], v[150:153], v[210:213], v[94:97]
	v_mfma_f32_16x16x32_bf16 v[90:93], v[166:169], v[210:213], v[90:93]
	v_mfma_f32_16x16x32_bf16 v[78:81], v[150:153], v[218:221], v[78:81]
	v_mfma_f32_16x16x32_bf16 v[74:77], v[166:169], v[218:221], v[74:77]
	v_mfma_f32_16x16x32_bf16 v[126:129], v[162:165], v[198:201], v[126:129]
	v_mfma_f32_16x16x32_bf16 v[122:125], v[170:173], v[198:201], v[122:125]
	v_mfma_f32_16x16x32_bf16 v[110:113], v[162:165], v[206:209], v[110:113]
	v_mfma_f32_16x16x32_bf16 v[106:109], v[170:173], v[206:209], v[106:109]
	v_mfma_f32_16x16x32_bf16 v[94:97], v[162:165], v[214:217], v[94:97]
	v_mfma_f32_16x16x32_bf16 v[90:93], v[170:173], v[214:217], v[90:93]
	v_mfma_f32_16x16x32_bf16 v[78:81], v[162:165], v[222:225], v[78:81]
	v_mfma_f32_16x16x32_bf16 v[74:77], v[170:173], v[222:225], v[74:77]
	v_mfma_f32_16x16x32_bf16 v[118:121], v[178:181], v[194:197], v[118:121]
	v_mfma_f32_16x16x32_bf16 v[114:117], v[186:189], v[194:197], v[114:117]
	v_mfma_f32_16x16x32_bf16 v[102:105], v[178:181], v[202:205], v[102:105]
	v_mfma_f32_16x16x32_bf16 v[98:101], v[186:189], v[202:205], v[98:101]
	v_mfma_f32_16x16x32_bf16 v[86:89], v[178:181], v[210:213], v[86:89]
	v_mfma_f32_16x16x32_bf16 v[82:85], v[186:189], v[210:213], v[82:85]
	v_mfma_f32_16x16x32_bf16 v[70:73], v[178:181], v[218:221], v[70:73]
	v_mfma_f32_16x16x32_bf16 v[66:69], v[186:189], v[218:221], v[66:69]
	v_mfma_f32_16x16x32_bf16 v[118:121], v[182:185], v[198:201], v[118:121]
	v_mfma_f32_16x16x32_bf16 v[114:117], v[190:193], v[198:201], v[114:117]
	v_mfma_f32_16x16x32_bf16 v[102:105], v[182:185], v[206:209], v[102:105]
	v_mfma_f32_16x16x32_bf16 v[98:101], v[190:193], v[206:209], v[98:101]
	v_mfma_f32_16x16x32_bf16 v[86:89], v[182:185], v[214:217], v[86:89]
	v_mfma_f32_16x16x32_bf16 v[82:85], v[190:193], v[214:217], v[82:85]
	v_mfma_f32_16x16x32_bf16 v[70:73], v[182:185], v[222:225], v[70:73]
	v_mfma_f32_16x16x32_bf16 v[66:69], v[190:193], v[222:225], v[66:69]
	s_barrier
	s_add_i32 s40, s51, s42
	v_lshl_add_u64 v[174:175], v[174:175], 0, s[12:13]
	s_mov_b32 m0, s40
	ds_read_b128 v[194:197], v161 offset:49152
	ds_read_b128 v[198:201], v161 offset:50176
	ds_read_b128 v[202:205], v161 offset:51200
	ds_read_b128 v[206:209], v161 offset:52224
	ds_read_b128 v[210:213], v161 offset:53248
	ds_read_b128 v[214:217], v161 offset:54272
	ds_read_b128 v[218:221], v161 offset:55296
	ds_read_b128 v[222:225], v161 offset:56320
	global_load_lds_dwordx4 v[174:175], off
	s_add_i32 m0, s40, 0x2000
	s_add_u32 s38, s38, 0x40080
	v_lshl_add_u64 v[174:175], v[226:227], 0, s[12:13]
	s_addc_u32 s39, s39, 0
	s_add_i32 s40, s52, s42
	global_load_lds_dwordx4 v[174:175], off
	v_lshl_add_u64 v[174:175], s[38:39], 0, v[132:133]
	s_mov_b32 m0, s40
	s_nop 0
	global_load_lds_dwordx4 v[174:175], off
	v_lshl_add_u64 v[174:175], s[38:39], 0, v[136:137]
	s_add_i32 m0, s40, 0x2000
	s_nop 0
	global_load_lds_dwordx4 v[174:175], off
	v_lshl_add_u64 v[174:175], v[228:229], 0, s[12:13]
	s_mov_b32 m0, s46
	s_nop 0
	global_load_lds_dwordx4 v[174:175], off
	v_lshl_add_u64 v[174:175], v[230:231], 0, s[12:13]
	s_mov_b32 m0, s47
	s_nop 0
	global_load_lds_dwordx4 v[174:175], off
	s_waitcnt vmcnt(8)
	s_waitcnt lgkmcnt(0)
	s_barrier
	s_waitcnt lgkmcnt(0)
	v_mfma_f32_16x16x32_bf16 v[62:65], v[150:153], v[194:197], v[62:65]
	v_mfma_f32_16x16x32_bf16 v[58:61], v[166:169], v[194:197], v[58:61]
	v_mfma_f32_16x16x32_bf16 v[46:49], v[150:153], v[202:205], v[46:49]
	v_mfma_f32_16x16x32_bf16 v[42:45], v[166:169], v[202:205], v[42:45]
	v_mfma_f32_16x16x32_bf16 v[30:33], v[150:153], v[210:213], v[30:33]
	v_mfma_f32_16x16x32_bf16 v[26:29], v[166:169], v[210:213], v[26:29]
	v_mfma_f32_16x16x32_bf16 v[14:17], v[150:153], v[218:221], v[14:17]
	v_mfma_f32_16x16x32_bf16 v[10:13], v[166:169], v[218:221], v[10:13]
	v_mfma_f32_16x16x32_bf16 v[62:65], v[162:165], v[198:201], v[62:65]
	v_mfma_f32_16x16x32_bf16 v[58:61], v[170:173], v[198:201], v[58:61]
	v_mfma_f32_16x16x32_bf16 v[46:49], v[162:165], v[206:209], v[46:49]
	v_mfma_f32_16x16x32_bf16 v[42:45], v[170:173], v[206:209], v[42:45]
	v_mfma_f32_16x16x32_bf16 v[30:33], v[162:165], v[214:217], v[30:33]
	v_mfma_f32_16x16x32_bf16 v[26:29], v[170:173], v[214:217], v[26:29]
	v_mfma_f32_16x16x32_bf16 v[14:17], v[162:165], v[222:225], v[14:17]
	v_mfma_f32_16x16x32_bf16 v[10:13], v[170:173], v[222:225], v[10:13]
	v_mfma_f32_16x16x32_bf16 v[54:57], v[178:181], v[194:197], v[54:57]
	v_mfma_f32_16x16x32_bf16 v[50:53], v[186:189], v[194:197], v[50:53]
	v_mfma_f32_16x16x32_bf16 v[38:41], v[178:181], v[202:205], v[38:41]
	v_mfma_f32_16x16x32_bf16 v[34:37], v[186:189], v[202:205], v[34:37]
	v_mfma_f32_16x16x32_bf16 v[22:25], v[178:181], v[210:213], v[22:25]
	v_mfma_f32_16x16x32_bf16 v[18:21], v[186:189], v[210:213], v[18:21]
	v_mfma_f32_16x16x32_bf16 v[6:9], v[178:181], v[218:221], v[6:9]
	v_mfma_f32_16x16x32_bf16 v[2:5], v[186:189], v[218:221], v[2:5]
	v_mfma_f32_16x16x32_bf16 v[54:57], v[182:185], v[198:201], v[54:57]
	v_mfma_f32_16x16x32_bf16 v[50:53], v[190:193], v[198:201], v[50:53]
	v_mfma_f32_16x16x32_bf16 v[38:41], v[182:185], v[206:209], v[38:41]
	v_mfma_f32_16x16x32_bf16 v[34:37], v[190:193], v[206:209], v[34:37]
	v_mfma_f32_16x16x32_bf16 v[22:25], v[182:185], v[214:217], v[22:25]
	v_mfma_f32_16x16x32_bf16 v[18:21], v[190:193], v[214:217], v[18:21]
	v_mfma_f32_16x16x32_bf16 v[6:9], v[182:185], v[222:225], v[6:9]
	v_mfma_f32_16x16x32_bf16 v[2:5], v[190:193], v[222:225], v[2:5]
	s_barrier
	s_add_i32 s66, s66, 2
	s_add_u32 s36, s36, 0x100
	s_addc_u32 s37, s37, 0
	s_add_u32 s64, s64, 0x100
	s_addc_u32 s65, s65, 0
	s_cmp_lt_u32 s67, 14
	s_cbranch_scc0 .LBB0_713

.LBB0_791:
	v_add_u32_e32 v153, s47, v151
	ds_read_b128 v[154:157], v153
	ds_read_b128 v[158:161], v153 offset:1024
	ds_read_b128 v[162:165], v153 offset:2048
	ds_read_b128 v[166:169], v153 offset:3072
	v_add_u32_e32 v153, s48, v151
	s_add_u32 s34, s12, s30
	ds_read_b128 v[170:173], v153
	ds_read_b128 v[180:183], v153 offset:1024
	ds_read_b128 v[184:187], v153 offset:2048
	ds_read_b128 v[188:191], v153 offset:3072
	s_addc_u32 s35, s13, s31
	s_add_u32 s34, s34, 0x100
	s_addc_u32 s35, s35, 0
	s_add_u32 s55, s50, s30
	s_addc_u32 s56, s51, s31
	s_cmpk_eq_i32 s30, 0x700
	s_cselect_b32 s37, s25, s35
	s_cselect_b32 s36, s52, s34
	s_cselect_b32 s35, s17, s56
	s_cselect_b32 s34, s53, s55
	v_lshl_add_u64 v[174:175], v[144:145], 0, s[30:31]
	s_add_i32 m0, s1, 0xc000
	ds_read_b128 v[192:195], v152
	ds_read_b128 v[196:199], v152 offset:1024
	ds_read_b128 v[200:203], v152 offset:2048
	ds_read_b128 v[204:207], v152 offset:3072
	ds_read_b128 v[208:211], v152 offset:4096
	ds_read_b128 v[212:215], v152 offset:5120
	ds_read_b128 v[216:219], v152 offset:6144
	ds_read_b128 v[220:223], v152 offset:7168
	global_load_lds_dwordx4 v[174:175], off
	v_lshl_add_u64 v[174:175], v[146:147], 0, s[30:31]
	s_add_i32 m0, s1, 0xe000
	s_nop 0
	global_load_lds_dwordx4 v[174:175], off
	s_waitcnt vmcnt(8)
	s_waitcnt lgkmcnt(0)
	s_barrier
	s_waitcnt lgkmcnt(0)
	v_mfma_f32_16x16x32_bf16 v[124:127], v[154:157], v[192:195], v[124:127]
	v_mfma_f32_16x16x32_bf16 v[120:123], v[162:165], v[192:195], v[120:123]
	v_mfma_f32_16x16x32_bf16 v[116:119], v[154:157], v[200:203], v[116:119]
	v_mfma_f32_16x16x32_bf16 v[112:115], v[162:165], v[200:203], v[112:115]
	v_mfma_f32_16x16x32_bf16 v[108:111], v[154:157], v[208:211], v[108:111]
	v_mfma_f32_16x16x32_bf16 v[104:107], v[162:165], v[208:211], v[104:107]
	v_mfma_f32_16x16x32_bf16 v[100:103], v[154:157], v[216:219], v[100:103]
	v_mfma_f32_16x16x32_bf16 v[96:99], v[162:165], v[216:219], v[96:99]
	v_mfma_f32_16x16x32_bf16 v[124:127], v[158:161], v[196:199], v[124:127]
	v_mfma_f32_16x16x32_bf16 v[120:123], v[166:169], v[196:199], v[120:123]
	v_mfma_f32_16x16x32_bf16 v[116:119], v[158:161], v[204:207], v[116:119]
	v_mfma_f32_16x16x32_bf16 v[112:115], v[166:169], v[204:207], v[112:115]
	v_mfma_f32_16x16x32_bf16 v[108:111], v[158:161], v[212:215], v[108:111]
	v_mfma_f32_16x16x32_bf16 v[104:107], v[166:169], v[212:215], v[104:107]
	v_mfma_f32_16x16x32_bf16 v[100:103], v[158:161], v[220:223], v[100:103]
	v_mfma_f32_16x16x32_bf16 v[96:99], v[166:169], v[220:223], v[96:99]
	v_mfma_f32_16x16x32_bf16 v[68:71], v[170:173], v[192:195], v[68:71]
	v_mfma_f32_16x16x32_bf16 v[60:63], v[184:187], v[192:195], v[60:63]
	v_mfma_f32_16x16x32_bf16 v[52:55], v[170:173], v[200:203], v[52:55]
	v_mfma_f32_16x16x32_bf16 v[48:51], v[184:187], v[200:203], v[48:51]
	v_mfma_f32_16x16x32_bf16 v[44:47], v[170:173], v[208:211], v[44:47]
	v_mfma_f32_16x16x32_bf16 v[40:43], v[184:187], v[208:211], v[40:43]
	v_mfma_f32_16x16x32_bf16 v[36:39], v[170:173], v[216:219], v[36:39]
	v_mfma_f32_16x16x32_bf16 v[32:35], v[184:187], v[216:219], v[32:35]
	v_mfma_f32_16x16x32_bf16 v[68:71], v[180:183], v[196:199], v[68:71]
	v_mfma_f32_16x16x32_bf16 v[60:63], v[188:191], v[196:199], v[60:63]
	v_mfma_f32_16x16x32_bf16 v[52:55], v[180:183], v[204:207], v[52:55]
	v_mfma_f32_16x16x32_bf16 v[48:51], v[188:191], v[204:207], v[48:51]
	v_mfma_f32_16x16x32_bf16 v[44:47], v[180:183], v[212:215], v[44:47]
	v_mfma_f32_16x16x32_bf16 v[40:43], v[188:191], v[212:215], v[40:43]
	v_mfma_f32_16x16x32_bf16 v[36:39], v[180:183], v[220:223], v[36:39]
	v_mfma_f32_16x16x32_bf16 v[32:35], v[188:191], v[220:223], v[32:35]
	s_barrier
	s_add_i32 s55, s47, s40
	v_lshl_add_u64 v[174:175], s[34:35], 0, v[130:131]
	s_mov_b32 m0, s55
	ds_read_b128 v[192:195], v152 offset:16384
	ds_read_b128 v[196:199], v152 offset:17408
	ds_read_b128 v[200:203], v152 offset:18432
	ds_read_b128 v[204:207], v152 offset:19456
	ds_read_b128 v[208:211], v152 offset:20480
	ds_read_b128 v[212:215], v152 offset:21504
	ds_read_b128 v[216:219], v152 offset:22528
	ds_read_b128 v[220:223], v152 offset:23552
	global_load_lds_dwordx4 v[174:175], off
	s_add_i32 m0, s55, 0x2000
	s_add_u32 s56, s34, 0x40000
	v_lshl_add_u64 v[224:225], s[34:35], 0, v[134:135]
	s_addc_u32 s57, s35, 0
	s_add_i32 s55, s48, s40
	global_load_lds_dwordx4 v[224:225], off
	v_lshl_add_u64 v[226:227], s[56:57], 0, v[130:131]
	s_mov_b32 m0, s55
	v_lshl_add_u64 v[228:229], s[36:37], 0, v[132:133]
	global_load_lds_dwordx4 v[226:227], off
	v_lshl_add_u64 v[226:227], s[56:57], 0, v[134:135]
	s_add_i32 m0, s55, 0x2000
	s_nop 0
	global_load_lds_dwordx4 v[226:227], off
	v_lshl_add_u64 v[226:227], s[36:37], 0, v[128:129]
	s_mov_b32 m0, s1
	s_nop 0
	global_load_lds_dwordx4 v[226:227], off
	s_mov_b32 m0, s41
	s_nop 0
	global_load_lds_dwordx4 v[228:229], off
	s_waitcnt vmcnt(8)
	s_waitcnt lgkmcnt(0)
	s_barrier
	s_waitcnt lgkmcnt(0)
	v_mfma_f32_16x16x32_bf16 v[92:95], v[154:157], v[192:195], v[92:95]
	v_mfma_f32_16x16x32_bf16 v[88:91], v[162:165], v[192:195], v[88:91]
	v_mfma_f32_16x16x32_bf16 v[84:87], v[154:157], v[200:203], v[84:87]
	v_mfma_f32_16x16x32_bf16 v[80:83], v[162:165], v[200:203], v[80:83]
	v_mfma_f32_16x16x32_bf16 v[76:79], v[154:157], v[208:211], v[76:79]
	v_mfma_f32_16x16x32_bf16 v[72:75], v[162:165], v[208:211], v[72:75]
	v_mfma_f32_16x16x32_bf16 v[64:67], v[154:157], v[216:219], v[64:67]
	v_mfma_f32_16x16x32_bf16 v[56:59], v[162:165], v[216:219], v[56:59]
	v_mfma_f32_16x16x32_bf16 v[92:95], v[158:161], v[196:199], v[92:95]
	v_mfma_f32_16x16x32_bf16 v[88:91], v[166:169], v[196:199], v[88:91]
	v_mfma_f32_16x16x32_bf16 v[84:87], v[158:161], v[204:207], v[84:87]
	v_mfma_f32_16x16x32_bf16 v[80:83], v[166:169], v[204:207], v[80:83]
	v_mfma_f32_16x16x32_bf16 v[76:79], v[158:161], v[212:215], v[76:79]
	v_mfma_f32_16x16x32_bf16 v[72:75], v[166:169], v[212:215], v[72:75]
	v_mfma_f32_16x16x32_bf16 v[64:67], v[158:161], v[220:223], v[64:67]
	v_mfma_f32_16x16x32_bf16 v[56:59], v[166:169], v[220:223], v[56:59]
	v_mfma_f32_16x16x32_bf16 v[28:31], v[170:173], v[192:195], v[28:31]
	v_mfma_f32_16x16x32_bf16 v[24:27], v[184:187], v[192:195], v[24:27]
	v_mfma_f32_16x16x32_bf16 v[20:23], v[170:173], v[200:203], v[20:23]
	v_mfma_f32_16x16x32_bf16 v[16:19], v[184:187], v[200:203], v[16:19]
	v_mfma_f32_16x16x32_bf16 v[12:15], v[170:173], v[208:211], v[12:15]
	v_mfma_f32_16x16x32_bf16 v[8:11], v[184:187], v[208:211], v[8:11]
	v_mfma_f32_16x16x32_bf16 v[4:7], v[170:173], v[216:219], v[4:7]
	v_mfma_f32_16x16x32_bf16 v[0:3], v[184:187], v[216:219], v[0:3]
	v_mfma_f32_16x16x32_bf16 v[28:31], v[180:183], v[196:199], v[28:31]
	v_mfma_f32_16x16x32_bf16 v[24:27], v[188:191], v[196:199], v[24:27]
	v_mfma_f32_16x16x32_bf16 v[20:23], v[180:183], v[204:207], v[20:23]
	v_mfma_f32_16x16x32_bf16 v[16:19], v[188:191], v[204:207], v[16:19]
	v_mfma_f32_16x16x32_bf16 v[12:15], v[180:183], v[212:215], v[12:15]
	v_mfma_f32_16x16x32_bf16 v[8:11], v[188:191], v[212:215], v[8:11]
	v_mfma_f32_16x16x32_bf16 v[4:7], v[180:183], v[220:223], v[4:7]
	v_mfma_f32_16x16x32_bf16 v[0:3], v[188:191], v[220:223], v[0:3]
	s_barrier
	s_add_i32 s55, 0, 0x18000
	v_add_u32_e32 v153, s55, v151
	s_add_i32 s56, 0, 0x1c000
	ds_read_b128 v[154:157], v153
	ds_read_b128 v[158:161], v153 offset:1024
	ds_read_b128 v[162:165], v153 offset:2048
	ds_read_b128 v[166:169], v153 offset:3072
	v_add_u32_e32 v153, s56, v151
	ds_read_b128 v[170:173], v153
	ds_read_b128 v[180:183], v153 offset:1024
	ds_read_b128 v[184:187], v153 offset:2048
	ds_read_b128 v[188:191], v153 offset:3072
	s_add_u32 s36, s36, 0x40000
	s_addc_u32 s37, s37, 0
	s_mov_b32 m0, s42
	v_lshl_add_u64 v[230:231], s[36:37], 0, v[128:129]
	ds_read_b128 v[192:195], v152 offset:32768
	ds_read_b128 v[196:199], v152 offset:33792
	ds_read_b128 v[200:203], v152 offset:34816
	ds_read_b128 v[204:207], v152 offset:35840
	ds_read_b128 v[208:211], v152 offset:36864
	ds_read_b128 v[212:215], v152 offset:37888
	ds_read_b128 v[216:219], v152 offset:38912
	ds_read_b128 v[220:223], v152 offset:39936
	global_load_lds_dwordx4 v[230:231], off
	v_lshl_add_u64 v[230:231], s[36:37], 0, v[132:133]
	s_mov_b32 m0, s43
	s_nop 0
	global_load_lds_dwordx4 v[230:231], off
	s_waitcnt vmcnt(8)
	s_waitcnt lgkmcnt(0)
	s_barrier
	s_waitcnt lgkmcnt(0)
	v_mfma_f32_16x16x32_bf16 v[124:127], v[154:157], v[192:195], v[124:127]
	v_mfma_f32_16x16x32_bf16 v[120:123], v[162:165], v[192:195], v[120:123]
	v_mfma_f32_16x16x32_bf16 v[116:119], v[154:157], v[200:203], v[116:119]
	v_mfma_f32_16x16x32_bf16 v[112:115], v[162:165], v[200:203], v[112:115]
	v_mfma_f32_16x16x32_bf16 v[108:111], v[154:157], v[208:211], v[108:111]
	v_mfma_f32_16x16x32_bf16 v[104:107], v[162:165], v[208:211], v[104:107]
	v_mfma_f32_16x16x32_bf16 v[100:103], v[154:157], v[216:219], v[100:103]
	v_mfma_f32_16x16x32_bf16 v[96:99], v[162:165], v[216:219], v[96:99]
	v_mfma_f32_16x16x32_bf16 v[124:127], v[158:161], v[196:199], v[124:127]
	v_mfma_f32_16x16x32_bf16 v[120:123], v[166:169], v[196:199], v[120:123]
	v_mfma_f32_16x16x32_bf16 v[116:119], v[158:161], v[204:207], v[116:119]
	v_mfma_f32_16x16x32_bf16 v[112:115], v[166:169], v[204:207], v[112:115]
	v_mfma_f32_16x16x32_bf16 v[108:111], v[158:161], v[212:215], v[108:111]
	v_mfma_f32_16x16x32_bf16 v[104:107], v[166:169], v[212:215], v[104:107]
	v_mfma_f32_16x16x32_bf16 v[100:103], v[158:161], v[220:223], v[100:103]
	v_mfma_f32_16x16x32_bf16 v[96:99], v[166:169], v[220:223], v[96:99]
	v_mfma_f32_16x16x32_bf16 v[68:71], v[170:173], v[192:195], v[68:71]
	v_mfma_f32_16x16x32_bf16 v[60:63], v[184:187], v[192:195], v[60:63]
	v_mfma_f32_16x16x32_bf16 v[52:55], v[170:173], v[200:203], v[52:55]
	v_mfma_f32_16x16x32_bf16 v[48:51], v[184:187], v[200:203], v[48:51]
	v_mfma_f32_16x16x32_bf16 v[44:47], v[170:173], v[208:211], v[44:47]
	v_mfma_f32_16x16x32_bf16 v[40:43], v[184:187], v[208:211], v[40:43]
	v_mfma_f32_16x16x32_bf16 v[36:39], v[170:173], v[216:219], v[36:39]
	v_mfma_f32_16x16x32_bf16 v[32:35], v[184:187], v[216:219], v[32:35]
	v_mfma_f32_16x16x32_bf16 v[68:71], v[180:183], v[196:199], v[68:71]
	v_mfma_f32_16x16x32_bf16 v[60:63], v[188:191], v[196:199], v[60:63]
	v_mfma_f32_16x16x32_bf16 v[52:55], v[180:183], v[204:207], v[52:55]
	v_mfma_f32_16x16x32_bf16 v[48:51], v[188:191], v[204:207], v[48:51]
	v_mfma_f32_16x16x32_bf16 v[44:47], v[180:183], v[212:215], v[44:47]
	v_mfma_f32_16x16x32_bf16 v[40:43], v[188:191], v[212:215], v[40:43]
	v_mfma_f32_16x16x32_bf16 v[36:39], v[180:183], v[220:223], v[36:39]
	v_mfma_f32_16x16x32_bf16 v[32:35], v[188:191], v[220:223], v[32:35]
	s_barrier
	s_add_i32 s36, s55, s40
	v_lshl_add_u64 v[174:175], v[174:175], 0, s[14:15]
	s_mov_b32 m0, s36
	ds_read_b128 v[192:195], v152 offset:49152
	ds_read_b128 v[196:199], v152 offset:50176
	ds_read_b128 v[200:203], v152 offset:51200
	ds_read_b128 v[204:207], v152 offset:52224
	ds_read_b128 v[208:211], v152 offset:53248
	ds_read_b128 v[212:215], v152 offset:54272
	ds_read_b128 v[216:219], v152 offset:55296
	ds_read_b128 v[220:223], v152 offset:56320
	global_load_lds_dwordx4 v[174:175], off
	s_add_i32 m0, s36, 0x2000
	s_add_u32 s34, s34, 0x40080
	v_lshl_add_u64 v[174:175], v[224:225], 0, s[14:15]
	s_addc_u32 s35, s35, 0
	s_add_i32 s36, s56, s40
	global_load_lds_dwordx4 v[174:175], off
	v_lshl_add_u64 v[174:175], s[34:35], 0, v[130:131]
	s_mov_b32 m0, s36
	s_nop 0
	global_load_lds_dwordx4 v[174:175], off
	v_lshl_add_u64 v[174:175], s[34:35], 0, v[134:135]
	s_add_i32 m0, s36, 0x2000
	s_nop 0
	global_load_lds_dwordx4 v[174:175], off
	v_lshl_add_u64 v[174:175], v[226:227], 0, s[14:15]
	s_mov_b32 m0, s44
	s_nop 0
	global_load_lds_dwordx4 v[174:175], off
	v_lshl_add_u64 v[174:175], v[228:229], 0, s[14:15]
	s_mov_b32 m0, s45
	s_nop 0
	global_load_lds_dwordx4 v[174:175], off
	s_waitcnt vmcnt(8)
	s_waitcnt lgkmcnt(0)
	s_barrier
	s_waitcnt lgkmcnt(0)
	v_mfma_f32_16x16x32_bf16 v[92:95], v[154:157], v[192:195], v[92:95]
	v_mfma_f32_16x16x32_bf16 v[88:91], v[162:165], v[192:195], v[88:91]
	v_mfma_f32_16x16x32_bf16 v[84:87], v[154:157], v[200:203], v[84:87]
	v_mfma_f32_16x16x32_bf16 v[80:83], v[162:165], v[200:203], v[80:83]
	v_mfma_f32_16x16x32_bf16 v[76:79], v[154:157], v[208:211], v[76:79]
	v_mfma_f32_16x16x32_bf16 v[72:75], v[162:165], v[208:211], v[72:75]
	v_mfma_f32_16x16x32_bf16 v[64:67], v[154:157], v[216:219], v[64:67]
	v_mfma_f32_16x16x32_bf16 v[56:59], v[162:165], v[216:219], v[56:59]
	v_mfma_f32_16x16x32_bf16 v[92:95], v[158:161], v[196:199], v[92:95]
	v_mfma_f32_16x16x32_bf16 v[88:91], v[166:169], v[196:199], v[88:91]
	v_mfma_f32_16x16x32_bf16 v[84:87], v[158:161], v[204:207], v[84:87]
	v_mfma_f32_16x16x32_bf16 v[80:83], v[166:169], v[204:207], v[80:83]
	v_mfma_f32_16x16x32_bf16 v[76:79], v[158:161], v[212:215], v[76:79]
	v_mfma_f32_16x16x32_bf16 v[72:75], v[166:169], v[212:215], v[72:75]
	v_mfma_f32_16x16x32_bf16 v[64:67], v[158:161], v[220:223], v[64:67]
	v_mfma_f32_16x16x32_bf16 v[56:59], v[166:169], v[220:223], v[56:59]
	v_mfma_f32_16x16x32_bf16 v[28:31], v[170:173], v[192:195], v[28:31]
	v_mfma_f32_16x16x32_bf16 v[24:27], v[184:187], v[192:195], v[24:27]
	v_mfma_f32_16x16x32_bf16 v[20:23], v[170:173], v[200:203], v[20:23]
	v_mfma_f32_16x16x32_bf16 v[16:19], v[184:187], v[200:203], v[16:19]
	v_mfma_f32_16x16x32_bf16 v[12:15], v[170:173], v[208:211], v[12:15]
	v_mfma_f32_16x16x32_bf16 v[8:11], v[184:187], v[208:211], v[8:11]
	v_mfma_f32_16x16x32_bf16 v[4:7], v[170:173], v[216:219], v[4:7]
	v_mfma_f32_16x16x32_bf16 v[0:3], v[184:187], v[216:219], v[0:3]
	v_mfma_f32_16x16x32_bf16 v[28:31], v[180:183], v[196:199], v[28:31]
	v_mfma_f32_16x16x32_bf16 v[24:27], v[188:191], v[196:199], v[24:27]
	v_mfma_f32_16x16x32_bf16 v[20:23], v[180:183], v[204:207], v[20:23]
	v_mfma_f32_16x16x32_bf16 v[16:19], v[188:191], v[204:207], v[16:19]
	v_mfma_f32_16x16x32_bf16 v[12:15], v[180:183], v[212:215], v[12:15]
	v_mfma_f32_16x16x32_bf16 v[8:11], v[188:191], v[212:215], v[8:11]
	v_mfma_f32_16x16x32_bf16 v[4:7], v[180:183], v[220:223], v[4:7]
	v_mfma_f32_16x16x32_bf16 v[0:3], v[188:191], v[220:223], v[0:3]
	s_barrier
	s_add_i32 s54, s54, 2
	s_add_u32 s30, s30, 0x100
	s_addc_u32 s31, s31, 0
	s_cmp_gt_u32 s54, 13
	s_cbranch_scc0 .LBB0_791
	s_add_u32 s30, s50, 0xffffff00
	s_addc_u32 s31, s51, -1
	s_andn2_b64 vcc, exec, s[8:9]
	s_cbranch_vccnz .LBB0_794
	v_mov_b32_e32 v0, 0
	s_mov_b32 s10, s16
	s_mov_b32 s0, s24
	s_mov_b64 s[12:13], s[28:29]
	s_mov_b32 s46, s49
	v_mov_b32_e32 v1, v0
	v_mov_b32_e32 v2, v0
	v_mov_b32_e32 v3, v0
	v_mov_b32_e32 v4, v0
	v_mov_b32_e32 v5, v0
	v_mov_b32_e32 v6, v0
	v_mov_b32_e32 v7, v0
	v_mov_b32_e32 v8, v0
	v_mov_b32_e32 v9, v0
	v_mov_b32_e32 v10, v0
	v_mov_b32_e32 v11, v0
	v_mov_b32_e32 v12, v0
	v_mov_b32_e32 v13, v0
	v_mov_b32_e32 v14, v0
	v_mov_b32_e32 v15, v0
	v_mov_b32_e32 v16, v0
	v_mov_b32_e32 v17, v0
	v_mov_b32_e32 v18, v0
	v_mov_b32_e32 v19, v0
	v_mov_b32_e32 v20, v0
	v_mov_b32_e32 v21, v0
	v_mov_b32_e32 v22, v0
	v_mov_b32_e32 v23, v0
	v_mov_b32_e32 v24, v0
	v_mov_b32_e32 v25, v0
	v_mov_b32_e32 v26, v0
	v_mov_b32_e32 v27, v0
	v_mov_b32_e32 v28, v0
	v_mov_b32_e32 v29, v0
	v_mov_b32_e32 v30, v0
	v_mov_b32_e32 v31, v0
	v_mov_b32_e32 v56, v0
	v_mov_b32_e32 v57, v0
	v_mov_b32_e32 v58, v0
	v_mov_b32_e32 v59, v0
	v_mov_b32_e32 v64, v0
	v_mov_b32_e32 v65, v0
	v_mov_b32_e32 v66, v0
	v_mov_b32_e32 v67, v0
	v_mov_b32_e32 v72, v0
	v_mov_b32_e32 v73, v0
	v_mov_b32_e32 v74, v0
	v_mov_b32_e32 v75, v0
	v_mov_b32_e32 v76, v0
	v_mov_b32_e32 v77, v0
	v_mov_b32_e32 v78, v0
	v_mov_b32_e32 v79, v0
	v_mov_b32_e32 v80, v0
	v_mov_b32_e32 v81, v0
	v_mov_b32_e32 v82, v0
	v_mov_b32_e32 v83, v0
	v_mov_b32_e32 v84, v0
	v_mov_b32_e32 v85, v0
	v_mov_b32_e32 v86, v0
	v_mov_b32_e32 v87, v0
	v_mov_b32_e32 v88, v0
	v_mov_b32_e32 v89, v0
	v_mov_b32_e32 v90, v0
	v_mov_b32_e32 v91, v0
	v_mov_b32_e32 v92, v0
	v_mov_b32_e32 v93, v0
	v_mov_b32_e32 v94, v0
	v_mov_b32_e32 v95, v0
	v_mov_b32_e32 v32, v0
	v_mov_b32_e32 v33, v0
	v_mov_b32_e32 v34, v0
	v_mov_b32_e32 v35, v0
	v_mov_b32_e32 v36, v0
	v_mov_b32_e32 v37, v0
	v_mov_b32_e32 v38, v0
	v_mov_b32_e32 v39, v0
	v_mov_b32_e32 v40, v0
	v_mov_b32_e32 v41, v0
	v_mov_b32_e32 v42, v0
	v_mov_b32_e32 v43, v0
	v_mov_b32_e32 v44, v0
	v_mov_b32_e32 v45, v0
	v_mov_b32_e32 v46, v0
	v_mov_b32_e32 v47, v0
	v_mov_b32_e32 v48, v0
	v_mov_b32_e32 v49, v0
	v_mov_b32_e32 v50, v0
	v_mov_b32_e32 v51, v0
	v_mov_b32_e32 v52, v0
	v_mov_b32_e32 v53, v0
	v_mov_b32_e32 v54, v0
	v_mov_b32_e32 v55, v0
	v_mov_b32_e32 v60, v0
	v_mov_b32_e32 v61, v0
	v_mov_b32_e32 v62, v0
	v_mov_b32_e32 v63, v0
	v_mov_b32_e32 v68, v0
	v_mov_b32_e32 v69, v0
	v_mov_b32_e32 v70, v0
	v_mov_b32_e32 v71, v0
	v_mov_b32_e32 v96, v0
	v_mov_b32_e32 v97, v0
	v_mov_b32_e32 v98, v0
	v_mov_b32_e32 v99, v0
	v_mov_b32_e32 v100, v0
	v_mov_b32_e32 v101, v0
	v_mov_b32_e32 v102, v0
	v_mov_b32_e32 v103, v0
	v_mov_b32_e32 v104, v0
	v_mov_b32_e32 v105, v0
	v_mov_b32_e32 v106, v0
	v_mov_b32_e32 v107, v0
	v_mov_b32_e32 v108, v0
	v_mov_b32_e32 v109, v0
	v_mov_b32_e32 v110, v0
	v_mov_b32_e32 v111, v0
	v_mov_b32_e32 v112, v0
	v_mov_b32_e32 v113, v0
	v_mov_b32_e32 v114, v0
	v_mov_b32_e32 v115, v0
	v_mov_b32_e32 v116, v0
	v_mov_b32_e32 v117, v0
	v_mov_b32_e32 v118, v0
	v_mov_b32_e32 v119, v0
	v_mov_b32_e32 v120, v0
	v_mov_b32_e32 v121, v0
	v_mov_b32_e32 v122, v0
	v_mov_b32_e32 v123, v0
	v_mov_b32_e32 v124, v0
	v_mov_b32_e32 v125, v0
	v_mov_b32_e32 v126, v0
	v_mov_b32_e32 v127, v0
	s_andn2_b64 vcc, exec, s[6:7]
	s_cbranch_vccnz .LBB0_795
	s_branch .LBB0_796

.LBB0_1079:
	ds_read_b128 v[156:159], v150
	ds_read_b128 v[160:163], v150 offset:1024
	ds_read_b128 v[164:167], v150 offset:2048
	ds_read_b128 v[168:171], v150 offset:3072
	ds_read_b128 v[172:175], v151
	ds_read_b128 v[178:181], v151 offset:1024
	ds_read_b128 v[182:185], v151 offset:2048
	ds_read_b128 v[186:189], v151 offset:3072
	s_add_u32 s34, s30, 0xfffc0080
	s_addc_u32 s35, s31, -1
	s_cmp_eq_u32 s54, 12
	s_cselect_b32 s37, s23, s35
	s_cselect_b32 s36, s50, s34
	s_cselect_b32 s35, s17, s53
	s_cselect_b32 s34, s51, s52
	v_lshl_add_u64 v[144:145], s[30:31], 0, v[136:137]
	s_add_i32 m0, s29, 0xc000
	ds_read_b128 v[190:193], v152
	ds_read_b128 v[194:197], v152 offset:1024
	ds_read_b128 v[198:201], v152 offset:2048
	ds_read_b128 v[202:205], v152 offset:3072
	ds_read_b128 v[206:209], v152 offset:4096
	ds_read_b128 v[210:213], v152 offset:5120
	ds_read_b128 v[214:217], v152 offset:6144
	ds_read_b128 v[218:221], v152 offset:7168
	global_load_lds_dwordx4 v[144:145], off
	v_lshl_add_u64 v[144:145], s[30:31], 0, v[138:139]
	s_add_i32 m0, s29, 0xe000
	s_nop 0
	global_load_lds_dwordx4 v[144:145], off
	s_waitcnt vmcnt(8)
	s_waitcnt lgkmcnt(0)
	s_barrier
	s_waitcnt lgkmcnt(0)
	v_mfma_f32_16x16x32_bf16 v[124:127], v[156:159], v[190:193], v[124:127]
	v_mfma_f32_16x16x32_bf16 v[120:123], v[164:167], v[190:193], v[120:123]
	v_mfma_f32_16x16x32_bf16 v[108:111], v[156:159], v[198:201], v[108:111]
	v_mfma_f32_16x16x32_bf16 v[104:107], v[164:167], v[198:201], v[104:107]
	v_mfma_f32_16x16x32_bf16 v[92:95], v[156:159], v[206:209], v[92:95]
	v_mfma_f32_16x16x32_bf16 v[88:91], v[164:167], v[206:209], v[88:91]
	v_mfma_f32_16x16x32_bf16 v[76:79], v[156:159], v[214:217], v[76:79]
	v_mfma_f32_16x16x32_bf16 v[72:75], v[164:167], v[214:217], v[72:75]
	v_mfma_f32_16x16x32_bf16 v[124:127], v[160:163], v[194:197], v[124:127]
	v_mfma_f32_16x16x32_bf16 v[120:123], v[168:171], v[194:197], v[120:123]
	v_mfma_f32_16x16x32_bf16 v[108:111], v[160:163], v[202:205], v[108:111]
	v_mfma_f32_16x16x32_bf16 v[104:107], v[168:171], v[202:205], v[104:107]
	v_mfma_f32_16x16x32_bf16 v[92:95], v[160:163], v[210:213], v[92:95]
	v_mfma_f32_16x16x32_bf16 v[88:91], v[168:171], v[210:213], v[88:91]
	v_mfma_f32_16x16x32_bf16 v[76:79], v[160:163], v[218:221], v[76:79]
	v_mfma_f32_16x16x32_bf16 v[72:75], v[168:171], v[218:221], v[72:75]
	v_mfma_f32_16x16x32_bf16 v[116:119], v[172:175], v[190:193], v[116:119]
	v_mfma_f32_16x16x32_bf16 v[112:115], v[182:185], v[190:193], v[112:115]
	v_mfma_f32_16x16x32_bf16 v[100:103], v[172:175], v[198:201], v[100:103]
	v_mfma_f32_16x16x32_bf16 v[96:99], v[182:185], v[198:201], v[96:99]
	v_mfma_f32_16x16x32_bf16 v[84:87], v[172:175], v[206:209], v[84:87]
	v_mfma_f32_16x16x32_bf16 v[80:83], v[182:185], v[206:209], v[80:83]
	v_mfma_f32_16x16x32_bf16 v[68:71], v[172:175], v[214:217], v[68:71]
	v_mfma_f32_16x16x32_bf16 v[64:67], v[182:185], v[214:217], v[64:67]
	v_mfma_f32_16x16x32_bf16 v[116:119], v[178:181], v[194:197], v[116:119]
	v_mfma_f32_16x16x32_bf16 v[112:115], v[186:189], v[194:197], v[112:115]
	v_mfma_f32_16x16x32_bf16 v[100:103], v[178:181], v[202:205], v[100:103]
	v_mfma_f32_16x16x32_bf16 v[96:99], v[186:189], v[202:205], v[96:99]
	v_mfma_f32_16x16x32_bf16 v[84:87], v[178:181], v[210:213], v[84:87]
	v_mfma_f32_16x16x32_bf16 v[80:83], v[186:189], v[210:213], v[80:83]
	v_mfma_f32_16x16x32_bf16 v[68:71], v[178:181], v[218:221], v[68:71]
	v_mfma_f32_16x16x32_bf16 v[64:67], v[186:189], v[218:221], v[64:67]
	s_barrier
	s_add_i32 s55, s45, s3
	v_lshl_add_u64 v[144:145], s[34:35], 0, v[130:131]
	s_mov_b32 m0, s55
	ds_read_b128 v[190:193], v152 offset:16384
	ds_read_b128 v[194:197], v152 offset:17408
	ds_read_b128 v[198:201], v152 offset:18432
	ds_read_b128 v[202:205], v152 offset:19456
	ds_read_b128 v[206:209], v152 offset:20480
	ds_read_b128 v[210:213], v152 offset:21504
	ds_read_b128 v[214:217], v152 offset:22528
	ds_read_b128 v[218:221], v152 offset:23552
	global_load_lds_dwordx4 v[144:145], off
	s_add_i32 m0, s55, 0x2000
	s_add_u32 s56, s34, 0x40000
	v_lshl_add_u64 v[222:223], s[34:35], 0, v[134:135]
	s_addc_u32 s57, s35, 0
	s_add_i32 s55, s46, s3
	global_load_lds_dwordx4 v[222:223], off
	v_lshl_add_u64 v[224:225], s[56:57], 0, v[130:131]
	s_mov_b32 m0, s55
	v_lshl_add_u64 v[226:227], s[36:37], 0, v[132:133]
	global_load_lds_dwordx4 v[224:225], off
	v_lshl_add_u64 v[224:225], s[56:57], 0, v[134:135]
	s_add_i32 m0, s55, 0x2000
	s_nop 0
	global_load_lds_dwordx4 v[224:225], off
	v_lshl_add_u64 v[224:225], s[36:37], 0, v[128:129]
	s_mov_b32 m0, s29
	s_nop 0
	global_load_lds_dwordx4 v[224:225], off
	s_mov_b32 m0, s33
	s_nop 0
	global_load_lds_dwordx4 v[226:227], off
	s_waitcnt vmcnt(8)
	s_waitcnt lgkmcnt(0)
	s_barrier
	s_waitcnt lgkmcnt(0)
	v_mfma_f32_16x16x32_bf16 v[60:63], v[156:159], v[190:193], v[60:63]
	v_mfma_f32_16x16x32_bf16 v[56:59], v[164:167], v[190:193], v[56:59]
	v_mfma_f32_16x16x32_bf16 v[44:47], v[156:159], v[198:201], v[44:47]
	v_mfma_f32_16x16x32_bf16 v[40:43], v[164:167], v[198:201], v[40:43]
	v_mfma_f32_16x16x32_bf16 v[28:31], v[156:159], v[206:209], v[28:31]
	v_mfma_f32_16x16x32_bf16 v[24:27], v[164:167], v[206:209], v[24:27]
	v_mfma_f32_16x16x32_bf16 v[12:15], v[156:159], v[214:217], v[12:15]
	v_mfma_f32_16x16x32_bf16 v[8:11], v[164:167], v[214:217], v[8:11]
	v_mfma_f32_16x16x32_bf16 v[60:63], v[160:163], v[194:197], v[60:63]
	v_mfma_f32_16x16x32_bf16 v[56:59], v[168:171], v[194:197], v[56:59]
	v_mfma_f32_16x16x32_bf16 v[44:47], v[160:163], v[202:205], v[44:47]
	v_mfma_f32_16x16x32_bf16 v[40:43], v[168:171], v[202:205], v[40:43]
	v_mfma_f32_16x16x32_bf16 v[28:31], v[160:163], v[210:213], v[28:31]
	v_mfma_f32_16x16x32_bf16 v[24:27], v[168:171], v[210:213], v[24:27]
	v_mfma_f32_16x16x32_bf16 v[12:15], v[160:163], v[218:221], v[12:15]
	v_mfma_f32_16x16x32_bf16 v[8:11], v[168:171], v[218:221], v[8:11]
	v_mfma_f32_16x16x32_bf16 v[52:55], v[172:175], v[190:193], v[52:55]
	v_mfma_f32_16x16x32_bf16 v[48:51], v[182:185], v[190:193], v[48:51]
	v_mfma_f32_16x16x32_bf16 v[36:39], v[172:175], v[198:201], v[36:39]
	v_mfma_f32_16x16x32_bf16 v[32:35], v[182:185], v[198:201], v[32:35]
	v_mfma_f32_16x16x32_bf16 v[20:23], v[172:175], v[206:209], v[20:23]
	v_mfma_f32_16x16x32_bf16 v[16:19], v[182:185], v[206:209], v[16:19]
	v_mfma_f32_16x16x32_bf16 v[4:7], v[172:175], v[214:217], v[4:7]
	v_mfma_f32_16x16x32_bf16 v[0:3], v[182:185], v[214:217], v[0:3]
	v_mfma_f32_16x16x32_bf16 v[52:55], v[178:181], v[194:197], v[52:55]
	v_mfma_f32_16x16x32_bf16 v[48:51], v[186:189], v[194:197], v[48:51]
	v_mfma_f32_16x16x32_bf16 v[36:39], v[178:181], v[202:205], v[36:39]
	v_mfma_f32_16x16x32_bf16 v[32:35], v[186:189], v[202:205], v[32:35]
	v_mfma_f32_16x16x32_bf16 v[20:23], v[178:181], v[210:213], v[20:23]
	v_mfma_f32_16x16x32_bf16 v[16:19], v[186:189], v[210:213], v[16:19]
	v_mfma_f32_16x16x32_bf16 v[4:7], v[178:181], v[218:221], v[4:7]
	v_mfma_f32_16x16x32_bf16 v[0:3], v[186:189], v[218:221], v[0:3]
	s_barrier
	ds_read_b128 v[156:159], v153
	ds_read_b128 v[160:163], v153 offset:1024
	ds_read_b128 v[164:167], v153 offset:2048
	ds_read_b128 v[168:171], v153 offset:3072
	ds_read_b128 v[172:175], v154
	ds_read_b128 v[178:181], v154 offset:1024
	ds_read_b128 v[182:185], v154 offset:2048
	ds_read_b128 v[186:189], v154 offset:3072
	s_add_u32 s36, s36, 0x40000
	s_addc_u32 s37, s37, 0
	s_mov_b32 m0, s38
	v_lshl_add_u64 v[228:229], s[36:37], 0, v[128:129]
	ds_read_b128 v[190:193], v152 offset:32768
	ds_read_b128 v[194:197], v152 offset:33792
	ds_read_b128 v[198:201], v152 offset:34816
	ds_read_b128 v[202:205], v152 offset:35840
	ds_read_b128 v[206:209], v152 offset:36864
	ds_read_b128 v[210:213], v152 offset:37888
	ds_read_b128 v[214:217], v152 offset:38912
	ds_read_b128 v[218:221], v152 offset:39936
	global_load_lds_dwordx4 v[228:229], off
	v_lshl_add_u64 v[228:229], s[36:37], 0, v[132:133]
	s_mov_b32 m0, s39
	s_nop 0
	global_load_lds_dwordx4 v[228:229], off
	s_waitcnt vmcnt(8)
	s_waitcnt lgkmcnt(0)
	s_barrier
	s_waitcnt lgkmcnt(0)
	v_mfma_f32_16x16x32_bf16 v[124:127], v[156:159], v[190:193], v[124:127]
	v_mfma_f32_16x16x32_bf16 v[120:123], v[164:167], v[190:193], v[120:123]
	v_mfma_f32_16x16x32_bf16 v[108:111], v[156:159], v[198:201], v[108:111]
	v_mfma_f32_16x16x32_bf16 v[104:107], v[164:167], v[198:201], v[104:107]
	v_mfma_f32_16x16x32_bf16 v[92:95], v[156:159], v[206:209], v[92:95]
	v_mfma_f32_16x16x32_bf16 v[88:91], v[164:167], v[206:209], v[88:91]
	v_mfma_f32_16x16x32_bf16 v[76:79], v[156:159], v[214:217], v[76:79]
	v_mfma_f32_16x16x32_bf16 v[72:75], v[164:167], v[214:217], v[72:75]
	v_mfma_f32_16x16x32_bf16 v[124:127], v[160:163], v[194:197], v[124:127]
	v_mfma_f32_16x16x32_bf16 v[120:123], v[168:171], v[194:197], v[120:123]
	v_mfma_f32_16x16x32_bf16 v[108:111], v[160:163], v[202:205], v[108:111]
	v_mfma_f32_16x16x32_bf16 v[104:107], v[168:171], v[202:205], v[104:107]
	v_mfma_f32_16x16x32_bf16 v[92:95], v[160:163], v[210:213], v[92:95]
	v_mfma_f32_16x16x32_bf16 v[88:91], v[168:171], v[210:213], v[88:91]
	v_mfma_f32_16x16x32_bf16 v[76:79], v[160:163], v[218:221], v[76:79]
	v_mfma_f32_16x16x32_bf16 v[72:75], v[168:171], v[218:221], v[72:75]
	v_mfma_f32_16x16x32_bf16 v[116:119], v[172:175], v[190:193], v[116:119]
	v_mfma_f32_16x16x32_bf16 v[112:115], v[182:185], v[190:193], v[112:115]
	v_mfma_f32_16x16x32_bf16 v[100:103], v[172:175], v[198:201], v[100:103]
	v_mfma_f32_16x16x32_bf16 v[96:99], v[182:185], v[198:201], v[96:99]
	v_mfma_f32_16x16x32_bf16 v[84:87], v[172:175], v[206:209], v[84:87]
	v_mfma_f32_16x16x32_bf16 v[80:83], v[182:185], v[206:209], v[80:83]
	v_mfma_f32_16x16x32_bf16 v[68:71], v[172:175], v[214:217], v[68:71]
	v_mfma_f32_16x16x32_bf16 v[64:67], v[182:185], v[214:217], v[64:67]
	v_mfma_f32_16x16x32_bf16 v[116:119], v[178:181], v[194:197], v[116:119]
	v_mfma_f32_16x16x32_bf16 v[112:115], v[186:189], v[194:197], v[112:115]
	v_mfma_f32_16x16x32_bf16 v[100:103], v[178:181], v[202:205], v[100:103]
	v_mfma_f32_16x16x32_bf16 v[96:99], v[186:189], v[202:205], v[96:99]
	v_mfma_f32_16x16x32_bf16 v[84:87], v[178:181], v[210:213], v[84:87]
	v_mfma_f32_16x16x32_bf16 v[80:83], v[186:189], v[210:213], v[80:83]
	v_mfma_f32_16x16x32_bf16 v[68:71], v[178:181], v[218:221], v[68:71]
	v_mfma_f32_16x16x32_bf16 v[64:67], v[186:189], v[218:221], v[64:67]
	s_barrier
	s_add_i32 s36, s47, s3
	v_lshl_add_u64 v[144:145], v[144:145], 0, s[12:13]
	s_mov_b32 m0, s36
	ds_read_b128 v[190:193], v152 offset:49152
	ds_read_b128 v[194:197], v152 offset:50176
	ds_read_b128 v[198:201], v152 offset:51200
	ds_read_b128 v[202:205], v152 offset:52224
	ds_read_b128 v[206:209], v152 offset:53248
	ds_read_b128 v[210:213], v152 offset:54272
	ds_read_b128 v[214:217], v152 offset:55296
	ds_read_b128 v[218:221], v152 offset:56320
	global_load_lds_dwordx4 v[144:145], off
	s_add_i32 m0, s36, 0x2000
	s_add_u32 s34, s34, 0x40080
	v_lshl_add_u64 v[144:145], v[222:223], 0, s[12:13]
	s_addc_u32 s35, s35, 0
	s_add_i32 s36, s48, s3
	global_load_lds_dwordx4 v[144:145], off
	v_lshl_add_u64 v[144:145], s[34:35], 0, v[130:131]
	s_mov_b32 m0, s36
	s_nop 0
	global_load_lds_dwordx4 v[144:145], off
	v_lshl_add_u64 v[144:145], s[34:35], 0, v[134:135]
	s_add_i32 m0, s36, 0x2000
	s_nop 0
	global_load_lds_dwordx4 v[144:145], off
	v_lshl_add_u64 v[144:145], v[224:225], 0, s[12:13]
	s_mov_b32 m0, s40
	s_nop 0
	global_load_lds_dwordx4 v[144:145], off
	v_lshl_add_u64 v[144:145], v[226:227], 0, s[12:13]
	s_mov_b32 m0, s41
	s_nop 0
	global_load_lds_dwordx4 v[144:145], off
	s_waitcnt vmcnt(8)
	s_waitcnt lgkmcnt(0)
	s_barrier
	s_waitcnt lgkmcnt(0)
	v_mfma_f32_16x16x32_bf16 v[60:63], v[156:159], v[190:193], v[60:63]
	v_mfma_f32_16x16x32_bf16 v[56:59], v[164:167], v[190:193], v[56:59]
	v_mfma_f32_16x16x32_bf16 v[44:47], v[156:159], v[198:201], v[44:47]
	v_mfma_f32_16x16x32_bf16 v[40:43], v[164:167], v[198:201], v[40:43]
	v_mfma_f32_16x16x32_bf16 v[28:31], v[156:159], v[206:209], v[28:31]
	v_mfma_f32_16x16x32_bf16 v[24:27], v[164:167], v[206:209], v[24:27]
	v_mfma_f32_16x16x32_bf16 v[12:15], v[156:159], v[214:217], v[12:15]
	v_mfma_f32_16x16x32_bf16 v[8:11], v[164:167], v[214:217], v[8:11]
	v_mfma_f32_16x16x32_bf16 v[60:63], v[160:163], v[194:197], v[60:63]
	v_mfma_f32_16x16x32_bf16 v[56:59], v[168:171], v[194:197], v[56:59]
	v_mfma_f32_16x16x32_bf16 v[44:47], v[160:163], v[202:205], v[44:47]
	v_mfma_f32_16x16x32_bf16 v[40:43], v[168:171], v[202:205], v[40:43]
	v_mfma_f32_16x16x32_bf16 v[28:31], v[160:163], v[210:213], v[28:31]
	v_mfma_f32_16x16x32_bf16 v[24:27], v[168:171], v[210:213], v[24:27]
	v_mfma_f32_16x16x32_bf16 v[12:15], v[160:163], v[218:221], v[12:15]
	v_mfma_f32_16x16x32_bf16 v[8:11], v[168:171], v[218:221], v[8:11]
	v_mfma_f32_16x16x32_bf16 v[52:55], v[172:175], v[190:193], v[52:55]
	v_mfma_f32_16x16x32_bf16 v[48:51], v[182:185], v[190:193], v[48:51]
	v_mfma_f32_16x16x32_bf16 v[36:39], v[172:175], v[198:201], v[36:39]
	v_mfma_f32_16x16x32_bf16 v[32:35], v[182:185], v[198:201], v[32:35]
	v_mfma_f32_16x16x32_bf16 v[20:23], v[172:175], v[206:209], v[20:23]
	v_mfma_f32_16x16x32_bf16 v[16:19], v[182:185], v[206:209], v[16:19]
	v_mfma_f32_16x16x32_bf16 v[4:7], v[172:175], v[214:217], v[4:7]
	v_mfma_f32_16x16x32_bf16 v[0:3], v[182:185], v[214:217], v[0:3]
	v_mfma_f32_16x16x32_bf16 v[52:55], v[178:181], v[194:197], v[52:55]
	v_mfma_f32_16x16x32_bf16 v[48:51], v[186:189], v[194:197], v[48:51]
	v_mfma_f32_16x16x32_bf16 v[36:39], v[178:181], v[202:205], v[36:39]
	v_mfma_f32_16x16x32_bf16 v[32:35], v[186:189], v[202:205], v[32:35]
	v_mfma_f32_16x16x32_bf16 v[20:23], v[178:181], v[210:213], v[20:23]
	v_mfma_f32_16x16x32_bf16 v[16:19], v[186:189], v[210:213], v[16:19]
	v_mfma_f32_16x16x32_bf16 v[4:7], v[178:181], v[218:221], v[4:7]
	v_mfma_f32_16x16x32_bf16 v[0:3], v[186:189], v[218:221], v[0:3]
	s_barrier
	s_add_i32 s54, s54, 2
	s_add_u32 s30, s30, 0x100
	s_addc_u32 s31, s31, 0
	s_add_u32 s52, s52, 0x100
	s_addc_u32 s53, s53, 0
	s_cmp_gt_u32 s54, 13
	s_cbranch_scc0 .LBB0_1079
	s_and_b64 vcc, exec, s[0:1]
	s_cbranch_vccz .LBB0_1082
	s_barrier

.LBB0_1158:
	v_add_u32_e32 v155, s46, v153
	ds_read_b128 v[156:159], v155
	ds_read_b128 v[160:163], v155 offset:1024
	ds_read_b128 v[164:167], v155 offset:2048
	ds_read_b128 v[168:171], v155 offset:3072
	v_add_u32_e32 v155, s47, v153
	s_add_u32 s30, s14, s28
	ds_read_b128 v[172:175], v155
	ds_read_b128 v[178:181], v155 offset:1024
	ds_read_b128 v[182:185], v155 offset:2048
	ds_read_b128 v[186:189], v155 offset:3072
	s_addc_u32 s31, s15, s29
	s_add_u32 s30, s30, 0x100
	s_addc_u32 s31, s31, 0
	s_add_u32 s54, s49, s28
	s_addc_u32 s55, s50, s29
	s_cmpk_eq_i32 s28, 0x1f00
	s_cselect_b32 s35, s23, s31
	s_cselect_b32 s34, s51, s30
	s_cselect_b32 s31, s21, s55
	s_cselect_b32 s30, s52, s54
	v_lshl_add_u64 v[222:223], v[144:145], 0, s[28:29]
	s_add_i32 m0, s13, 0xc000
	ds_read_b128 v[190:193], v154
	ds_read_b128 v[194:197], v154 offset:1024
	ds_read_b128 v[198:201], v154 offset:2048
	ds_read_b128 v[202:205], v154 offset:3072
	ds_read_b128 v[206:209], v154 offset:4096
	ds_read_b128 v[210:213], v154 offset:5120
	ds_read_b128 v[214:217], v154 offset:6144
	ds_read_b128 v[218:221], v154 offset:7168
	global_load_lds_dwordx4 v[222:223], off
	v_lshl_add_u64 v[222:223], v[146:147], 0, s[28:29]
	s_add_i32 m0, s13, 0xe000
	s_nop 0
	global_load_lds_dwordx4 v[222:223], off
	s_waitcnt vmcnt(8)
	s_waitcnt lgkmcnt(0)
	s_barrier
	s_waitcnt lgkmcnt(0)
	v_mfma_f32_16x16x32_bf16 v[124:127], v[156:159], v[190:193], v[124:127]
	v_mfma_f32_16x16x32_bf16 v[120:123], v[164:167], v[190:193], v[120:123]
	v_mfma_f32_16x16x32_bf16 v[116:119], v[156:159], v[198:201], v[116:119]
	v_mfma_f32_16x16x32_bf16 v[112:115], v[164:167], v[198:201], v[112:115]
	v_mfma_f32_16x16x32_bf16 v[108:111], v[156:159], v[206:209], v[108:111]
	v_mfma_f32_16x16x32_bf16 v[104:107], v[164:167], v[206:209], v[104:107]
	v_mfma_f32_16x16x32_bf16 v[100:103], v[156:159], v[214:217], v[100:103]
	v_mfma_f32_16x16x32_bf16 v[96:99], v[164:167], v[214:217], v[96:99]
	v_mfma_f32_16x16x32_bf16 v[124:127], v[160:163], v[194:197], v[124:127]
	v_mfma_f32_16x16x32_bf16 v[120:123], v[168:171], v[194:197], v[120:123]
	v_mfma_f32_16x16x32_bf16 v[116:119], v[160:163], v[202:205], v[116:119]
	v_mfma_f32_16x16x32_bf16 v[112:115], v[168:171], v[202:205], v[112:115]
	v_mfma_f32_16x16x32_bf16 v[108:111], v[160:163], v[210:213], v[108:111]
	v_mfma_f32_16x16x32_bf16 v[104:107], v[168:171], v[210:213], v[104:107]
	v_mfma_f32_16x16x32_bf16 v[100:103], v[160:163], v[218:221], v[100:103]
	v_mfma_f32_16x16x32_bf16 v[96:99], v[168:171], v[218:221], v[96:99]
	v_mfma_f32_16x16x32_bf16 v[76:79], v[172:175], v[190:193], v[76:79]
	v_mfma_f32_16x16x32_bf16 v[72:75], v[182:185], v[190:193], v[72:75]
	v_mfma_f32_16x16x32_bf16 v[60:63], v[172:175], v[198:201], v[60:63]
	v_mfma_f32_16x16x32_bf16 v[56:59], v[182:185], v[198:201], v[56:59]
	v_mfma_f32_16x16x32_bf16 v[44:47], v[172:175], v[206:209], v[44:47]
	v_mfma_f32_16x16x32_bf16 v[40:43], v[182:185], v[206:209], v[40:43]
	v_mfma_f32_16x16x32_bf16 v[36:39], v[172:175], v[214:217], v[36:39]
	v_mfma_f32_16x16x32_bf16 v[32:35], v[182:185], v[214:217], v[32:35]
	v_mfma_f32_16x16x32_bf16 v[76:79], v[178:181], v[194:197], v[76:79]
	v_mfma_f32_16x16x32_bf16 v[72:75], v[186:189], v[194:197], v[72:75]
	v_mfma_f32_16x16x32_bf16 v[60:63], v[178:181], v[202:205], v[60:63]
	v_mfma_f32_16x16x32_bf16 v[56:59], v[186:189], v[202:205], v[56:59]
	v_mfma_f32_16x16x32_bf16 v[44:47], v[178:181], v[210:213], v[44:47]
	v_mfma_f32_16x16x32_bf16 v[40:43], v[186:189], v[210:213], v[40:43]
	v_mfma_f32_16x16x32_bf16 v[36:39], v[178:181], v[218:221], v[36:39]
	v_mfma_f32_16x16x32_bf16 v[32:35], v[186:189], v[218:221], v[32:35]
	s_barrier
	s_add_i32 s54, s46, s39
	v_lshl_add_u64 v[222:223], s[30:31], 0, v[130:131]
	s_mov_b32 m0, s54
	ds_read_b128 v[190:193], v154 offset:16384
	ds_read_b128 v[194:197], v154 offset:17408
	ds_read_b128 v[198:201], v154 offset:18432
	ds_read_b128 v[202:205], v154 offset:19456
	ds_read_b128 v[206:209], v154 offset:20480
	ds_read_b128 v[210:213], v154 offset:21504
	ds_read_b128 v[214:217], v154 offset:22528
	ds_read_b128 v[218:221], v154 offset:23552
	global_load_lds_dwordx4 v[222:223], off
	s_add_i32 m0, s54, 0x2000
	s_add_u32 s54, s30, 0x100000
	v_lshl_add_u64 v[224:225], s[30:31], 0, v[134:135]
	s_addc_u32 s55, s31, 0
	s_add_i32 s56, s47, s39
	global_load_lds_dwordx4 v[224:225], off
	v_lshl_add_u64 v[226:227], s[54:55], 0, v[130:131]
	s_mov_b32 m0, s56
	v_lshl_add_u64 v[228:229], s[34:35], 0, v[132:133]
	global_load_lds_dwordx4 v[226:227], off
	v_lshl_add_u64 v[226:227], s[54:55], 0, v[134:135]
	s_add_i32 m0, s56, 0x2000
	s_nop 0
	global_load_lds_dwordx4 v[226:227], off
	v_lshl_add_u64 v[226:227], s[34:35], 0, v[128:129]
	s_mov_b32 m0, s13
	s_nop 0
	global_load_lds_dwordx4 v[226:227], off
	s_mov_b32 m0, s40
	s_nop 0
	global_load_lds_dwordx4 v[228:229], off
	s_waitcnt vmcnt(8)
	s_waitcnt lgkmcnt(0)
	s_barrier
	s_waitcnt lgkmcnt(0)
	v_mfma_f32_16x16x32_bf16 v[92:95], v[156:159], v[190:193], v[92:95]
	v_mfma_f32_16x16x32_bf16 v[88:91], v[164:167], v[190:193], v[88:91]
	v_mfma_f32_16x16x32_bf16 v[84:87], v[156:159], v[198:201], v[84:87]
	v_mfma_f32_16x16x32_bf16 v[80:83], v[164:167], v[198:201], v[80:83]
	v_mfma_f32_16x16x32_bf16 v[68:71], v[156:159], v[206:209], v[68:71]
	v_mfma_f32_16x16x32_bf16 v[64:67], v[164:167], v[206:209], v[64:67]
	v_mfma_f32_16x16x32_bf16 v[52:55], v[156:159], v[214:217], v[52:55]
	v_mfma_f32_16x16x32_bf16 v[48:51], v[164:167], v[214:217], v[48:51]
	v_mfma_f32_16x16x32_bf16 v[92:95], v[160:163], v[194:197], v[92:95]
	v_mfma_f32_16x16x32_bf16 v[88:91], v[168:171], v[194:197], v[88:91]
	v_mfma_f32_16x16x32_bf16 v[84:87], v[160:163], v[202:205], v[84:87]
	v_mfma_f32_16x16x32_bf16 v[80:83], v[168:171], v[202:205], v[80:83]
	v_mfma_f32_16x16x32_bf16 v[68:71], v[160:163], v[210:213], v[68:71]
	v_mfma_f32_16x16x32_bf16 v[64:67], v[168:171], v[210:213], v[64:67]
	v_mfma_f32_16x16x32_bf16 v[52:55], v[160:163], v[218:221], v[52:55]
	v_mfma_f32_16x16x32_bf16 v[48:51], v[168:171], v[218:221], v[48:51]
	v_mfma_f32_16x16x32_bf16 v[28:31], v[172:175], v[190:193], v[28:31]
	v_mfma_f32_16x16x32_bf16 v[24:27], v[182:185], v[190:193], v[24:27]
	v_mfma_f32_16x16x32_bf16 v[20:23], v[172:175], v[198:201], v[20:23]
	v_mfma_f32_16x16x32_bf16 v[16:19], v[182:185], v[198:201], v[16:19]
	v_mfma_f32_16x16x32_bf16 v[12:15], v[172:175], v[206:209], v[12:15]
	v_mfma_f32_16x16x32_bf16 v[8:11], v[182:185], v[206:209], v[8:11]
	v_mfma_f32_16x16x32_bf16 v[4:7], v[172:175], v[214:217], v[4:7]
	v_mfma_f32_16x16x32_bf16 v[0:3], v[182:185], v[214:217], v[0:3]
	v_mfma_f32_16x16x32_bf16 v[28:31], v[178:181], v[194:197], v[28:31]
	v_mfma_f32_16x16x32_bf16 v[24:27], v[186:189], v[194:197], v[24:27]
	v_mfma_f32_16x16x32_bf16 v[20:23], v[178:181], v[202:205], v[20:23]
	v_mfma_f32_16x16x32_bf16 v[16:19], v[186:189], v[202:205], v[16:19]
	v_mfma_f32_16x16x32_bf16 v[12:15], v[178:181], v[210:213], v[12:15]
	v_mfma_f32_16x16x32_bf16 v[8:11], v[186:189], v[210:213], v[8:11]
	v_mfma_f32_16x16x32_bf16 v[4:7], v[178:181], v[218:221], v[4:7]
	v_mfma_f32_16x16x32_bf16 v[0:3], v[186:189], v[218:221], v[0:3]
	s_barrier
	s_add_i32 s54, 0, 0x18000
	v_add_u32_e32 v155, s54, v153
	s_add_i32 s55, 0, 0x1c000
	ds_read_b128 v[156:159], v155
	ds_read_b128 v[160:163], v155 offset:1024
	ds_read_b128 v[164:167], v155 offset:2048
	ds_read_b128 v[168:171], v155 offset:3072
	v_add_u32_e32 v155, s55, v153
	ds_read_b128 v[172:175], v155
	ds_read_b128 v[178:181], v155 offset:1024
	ds_read_b128 v[182:185], v155 offset:2048
	ds_read_b128 v[186:189], v155 offset:3072
	s_add_u32 s34, s34, 0x100000
	s_addc_u32 s35, s35, 0
	s_mov_b32 m0, s41
	v_lshl_add_u64 v[230:231], s[34:35], 0, v[128:129]
	ds_read_b128 v[190:193], v154 offset:32768
	ds_read_b128 v[194:197], v154 offset:33792
	ds_read_b128 v[198:201], v154 offset:34816
	ds_read_b128 v[202:205], v154 offset:35840
	ds_read_b128 v[206:209], v154 offset:36864
	ds_read_b128 v[210:213], v154 offset:37888
	ds_read_b128 v[214:217], v154 offset:38912
	ds_read_b128 v[218:221], v154 offset:39936
	global_load_lds_dwordx4 v[230:231], off
	v_lshl_add_u64 v[230:231], s[34:35], 0, v[132:133]
	s_mov_b32 m0, s42
	s_nop 0
	global_load_lds_dwordx4 v[230:231], off
	s_waitcnt vmcnt(8)
	s_waitcnt lgkmcnt(0)
	s_barrier
	s_waitcnt lgkmcnt(0)
	v_mfma_f32_16x16x32_bf16 v[124:127], v[156:159], v[190:193], v[124:127]
	v_mfma_f32_16x16x32_bf16 v[120:123], v[164:167], v[190:193], v[120:123]
	v_mfma_f32_16x16x32_bf16 v[116:119], v[156:159], v[198:201], v[116:119]
	v_mfma_f32_16x16x32_bf16 v[112:115], v[164:167], v[198:201], v[112:115]
	v_mfma_f32_16x16x32_bf16 v[108:111], v[156:159], v[206:209], v[108:111]
	v_mfma_f32_16x16x32_bf16 v[104:107], v[164:167], v[206:209], v[104:107]
	v_mfma_f32_16x16x32_bf16 v[100:103], v[156:159], v[214:217], v[100:103]
	v_mfma_f32_16x16x32_bf16 v[96:99], v[164:167], v[214:217], v[96:99]
	v_mfma_f32_16x16x32_bf16 v[124:127], v[160:163], v[194:197], v[124:127]
	v_mfma_f32_16x16x32_bf16 v[120:123], v[168:171], v[194:197], v[120:123]
	v_mfma_f32_16x16x32_bf16 v[116:119], v[160:163], v[202:205], v[116:119]
	v_mfma_f32_16x16x32_bf16 v[112:115], v[168:171], v[202:205], v[112:115]
	v_mfma_f32_16x16x32_bf16 v[108:111], v[160:163], v[210:213], v[108:111]
	v_mfma_f32_16x16x32_bf16 v[104:107], v[168:171], v[210:213], v[104:107]
	v_mfma_f32_16x16x32_bf16 v[100:103], v[160:163], v[218:221], v[100:103]
	v_mfma_f32_16x16x32_bf16 v[96:99], v[168:171], v[218:221], v[96:99]
	v_mfma_f32_16x16x32_bf16 v[76:79], v[172:175], v[190:193], v[76:79]
	v_mfma_f32_16x16x32_bf16 v[72:75], v[182:185], v[190:193], v[72:75]
	v_mfma_f32_16x16x32_bf16 v[60:63], v[172:175], v[198:201], v[60:63]
	v_mfma_f32_16x16x32_bf16 v[56:59], v[182:185], v[198:201], v[56:59]
	v_mfma_f32_16x16x32_bf16 v[44:47], v[172:175], v[206:209], v[44:47]
	v_mfma_f32_16x16x32_bf16 v[40:43], v[182:185], v[206:209], v[40:43]
	v_mfma_f32_16x16x32_bf16 v[36:39], v[172:175], v[214:217], v[36:39]
	v_mfma_f32_16x16x32_bf16 v[32:35], v[182:185], v[214:217], v[32:35]
	v_mfma_f32_16x16x32_bf16 v[76:79], v[178:181], v[194:197], v[76:79]
	v_mfma_f32_16x16x32_bf16 v[72:75], v[186:189], v[194:197], v[72:75]
	v_mfma_f32_16x16x32_bf16 v[60:63], v[178:181], v[202:205], v[60:63]
	v_mfma_f32_16x16x32_bf16 v[56:59], v[186:189], v[202:205], v[56:59]
	v_mfma_f32_16x16x32_bf16 v[44:47], v[178:181], v[210:213], v[44:47]
	v_mfma_f32_16x16x32_bf16 v[40:43], v[186:189], v[210:213], v[40:43]
	v_mfma_f32_16x16x32_bf16 v[36:39], v[178:181], v[218:221], v[36:39]
	v_mfma_f32_16x16x32_bf16 v[32:35], v[186:189], v[218:221], v[32:35]
	s_barrier
	s_add_i32 s34, s54, s39
	v_lshl_add_u64 v[222:223], v[222:223], 0, s[16:17]
	s_mov_b32 m0, s34
	ds_read_b128 v[190:193], v154 offset:49152
	ds_read_b128 v[194:197], v154 offset:50176
	ds_read_b128 v[198:201], v154 offset:51200
	ds_read_b128 v[202:205], v154 offset:52224
	ds_read_b128 v[206:209], v154 offset:53248
	ds_read_b128 v[210:213], v154 offset:54272
	ds_read_b128 v[214:217], v154 offset:55296
	ds_read_b128 v[218:221], v154 offset:56320
	global_load_lds_dwordx4 v[222:223], off
	s_add_i32 m0, s34, 0x2000
	s_add_u32 s30, s30, 0x100080
	v_lshl_add_u64 v[222:223], v[224:225], 0, s[16:17]
	s_addc_u32 s31, s31, 0
	s_add_i32 s34, s55, s39
	global_load_lds_dwordx4 v[222:223], off
	v_lshl_add_u64 v[222:223], s[30:31], 0, v[130:131]
	s_mov_b32 m0, s34
	s_nop 0
	global_load_lds_dwordx4 v[222:223], off
	v_lshl_add_u64 v[222:223], s[30:31], 0, v[134:135]
	s_add_i32 m0, s34, 0x2000
	s_nop 0
	global_load_lds_dwordx4 v[222:223], off
	v_lshl_add_u64 v[222:223], v[226:227], 0, s[16:17]
	s_mov_b32 m0, s43
	s_nop 0
	global_load_lds_dwordx4 v[222:223], off
	v_lshl_add_u64 v[222:223], v[228:229], 0, s[16:17]
	s_mov_b32 m0, s44
	s_nop 0
	global_load_lds_dwordx4 v[222:223], off
	s_waitcnt vmcnt(8)
	s_waitcnt lgkmcnt(0)
	s_barrier
	s_waitcnt lgkmcnt(0)
	v_mfma_f32_16x16x32_bf16 v[92:95], v[156:159], v[190:193], v[92:95]
	v_mfma_f32_16x16x32_bf16 v[88:91], v[164:167], v[190:193], v[88:91]
	v_mfma_f32_16x16x32_bf16 v[84:87], v[156:159], v[198:201], v[84:87]
	v_mfma_f32_16x16x32_bf16 v[80:83], v[164:167], v[198:201], v[80:83]
	v_mfma_f32_16x16x32_bf16 v[68:71], v[156:159], v[206:209], v[68:71]
	v_mfma_f32_16x16x32_bf16 v[64:67], v[164:167], v[206:209], v[64:67]
	v_mfma_f32_16x16x32_bf16 v[52:55], v[156:159], v[214:217], v[52:55]
	v_mfma_f32_16x16x32_bf16 v[48:51], v[164:167], v[214:217], v[48:51]
	v_mfma_f32_16x16x32_bf16 v[92:95], v[160:163], v[194:197], v[92:95]
	v_mfma_f32_16x16x32_bf16 v[88:91], v[168:171], v[194:197], v[88:91]
	v_mfma_f32_16x16x32_bf16 v[84:87], v[160:163], v[202:205], v[84:87]
	v_mfma_f32_16x16x32_bf16 v[80:83], v[168:171], v[202:205], v[80:83]
	v_mfma_f32_16x16x32_bf16 v[68:71], v[160:163], v[210:213], v[68:71]
	v_mfma_f32_16x16x32_bf16 v[64:67], v[168:171], v[210:213], v[64:67]
	v_mfma_f32_16x16x32_bf16 v[52:55], v[160:163], v[218:221], v[52:55]
	v_mfma_f32_16x16x32_bf16 v[48:51], v[168:171], v[218:221], v[48:51]
	v_mfma_f32_16x16x32_bf16 v[28:31], v[172:175], v[190:193], v[28:31]
	v_mfma_f32_16x16x32_bf16 v[24:27], v[182:185], v[190:193], v[24:27]
	v_mfma_f32_16x16x32_bf16 v[20:23], v[172:175], v[198:201], v[20:23]
	v_mfma_f32_16x16x32_bf16 v[16:19], v[182:185], v[198:201], v[16:19]
	v_mfma_f32_16x16x32_bf16 v[12:15], v[172:175], v[206:209], v[12:15]
	v_mfma_f32_16x16x32_bf16 v[8:11], v[182:185], v[206:209], v[8:11]
	v_mfma_f32_16x16x32_bf16 v[4:7], v[172:175], v[214:217], v[4:7]
	v_mfma_f32_16x16x32_bf16 v[0:3], v[182:185], v[214:217], v[0:3]
	v_mfma_f32_16x16x32_bf16 v[28:31], v[178:181], v[194:197], v[28:31]
	v_mfma_f32_16x16x32_bf16 v[24:27], v[186:189], v[194:197], v[24:27]
	v_mfma_f32_16x16x32_bf16 v[20:23], v[178:181], v[202:205], v[20:23]
	v_mfma_f32_16x16x32_bf16 v[16:19], v[186:189], v[202:205], v[16:19]
	v_mfma_f32_16x16x32_bf16 v[12:15], v[178:181], v[210:213], v[12:15]
	v_mfma_f32_16x16x32_bf16 v[8:11], v[186:189], v[210:213], v[8:11]
	v_mfma_f32_16x16x32_bf16 v[4:7], v[178:181], v[218:221], v[4:7]
	v_mfma_f32_16x16x32_bf16 v[0:3], v[186:189], v[218:221], v[0:3]
	s_barrier
	s_add_i32 s53, s53, 2
	s_add_u32 s28, s28, 0x100
	s_addc_u32 s29, s29, 0
	s_cmp_gt_u32 s53, 61
	s_cbranch_scc0 .LBB0_1158
	s_add_u32 s28, s49, 0xffffff00
	s_addc_u32 s29, s50, -1
	s_andn2_b64 vcc, exec, s[6:7]
	s_cbranch_vccnz .LBB0_1161
	v_mov_b32_e32 v0, 0
	s_mov_b32 s10, s20
	s_mov_b32 s12, s22
	s_mov_b64 s[14:15], s[26:27]
	s_mov_b32 s45, s48
	v_mov_b32_e32 v1, v0
	v_mov_b32_e32 v2, v0
	v_mov_b32_e32 v3, v0
	v_mov_b32_e32 v4, v0
	v_mov_b32_e32 v5, v0
	v_mov_b32_e32 v6, v0
	v_mov_b32_e32 v7, v0
	v_mov_b32_e32 v8, v0
	v_mov_b32_e32 v9, v0
	v_mov_b32_e32 v10, v0
	v_mov_b32_e32 v11, v0
	v_mov_b32_e32 v12, v0
	v_mov_b32_e32 v13, v0
	v_mov_b32_e32 v14, v0
	v_mov_b32_e32 v15, v0
	v_mov_b32_e32 v16, v0
	v_mov_b32_e32 v17, v0
	v_mov_b32_e32 v18, v0
	v_mov_b32_e32 v19, v0
	v_mov_b32_e32 v20, v0
	v_mov_b32_e32 v21, v0
	v_mov_b32_e32 v22, v0
	v_mov_b32_e32 v23, v0
	v_mov_b32_e32 v24, v0
	v_mov_b32_e32 v25, v0
	v_mov_b32_e32 v26, v0
	v_mov_b32_e32 v27, v0
	v_mov_b32_e32 v28, v0
	v_mov_b32_e32 v29, v0
	v_mov_b32_e32 v30, v0
	v_mov_b32_e32 v31, v0
	v_mov_b32_e32 v48, v0
	v_mov_b32_e32 v49, v0
	v_mov_b32_e32 v50, v0
	v_mov_b32_e32 v51, v0
	v_mov_b32_e32 v52, v0
	v_mov_b32_e32 v53, v0
	v_mov_b32_e32 v54, v0
	v_mov_b32_e32 v55, v0
	v_mov_b32_e32 v64, v0
	v_mov_b32_e32 v65, v0
	v_mov_b32_e32 v66, v0
	v_mov_b32_e32 v67, v0
	v_mov_b32_e32 v68, v0
	v_mov_b32_e32 v69, v0
	v_mov_b32_e32 v70, v0
	v_mov_b32_e32 v71, v0
	v_mov_b32_e32 v80, v0
	v_mov_b32_e32 v81, v0
	v_mov_b32_e32 v82, v0
	v_mov_b32_e32 v83, v0
	v_mov_b32_e32 v84, v0
	v_mov_b32_e32 v85, v0
	v_mov_b32_e32 v86, v0
	v_mov_b32_e32 v87, v0
	v_mov_b32_e32 v88, v0
	v_mov_b32_e32 v89, v0
	v_mov_b32_e32 v90, v0
	v_mov_b32_e32 v91, v0
	v_mov_b32_e32 v92, v0
	v_mov_b32_e32 v93, v0
	v_mov_b32_e32 v94, v0
	v_mov_b32_e32 v95, v0
	v_mov_b32_e32 v32, v0
	v_mov_b32_e32 v33, v0
	v_mov_b32_e32 v34, v0
	v_mov_b32_e32 v35, v0
	v_mov_b32_e32 v36, v0
	v_mov_b32_e32 v37, v0
	v_mov_b32_e32 v38, v0
	v_mov_b32_e32 v39, v0
	v_mov_b32_e32 v40, v0
	v_mov_b32_e32 v41, v0
	v_mov_b32_e32 v42, v0
	v_mov_b32_e32 v43, v0
	v_mov_b32_e32 v44, v0
	v_mov_b32_e32 v45, v0
	v_mov_b32_e32 v46, v0
	v_mov_b32_e32 v47, v0
	v_mov_b32_e32 v56, v0
	v_mov_b32_e32 v57, v0
	v_mov_b32_e32 v58, v0
	v_mov_b32_e32 v59, v0
	v_mov_b32_e32 v60, v0
	v_mov_b32_e32 v61, v0
	v_mov_b32_e32 v62, v0
	v_mov_b32_e32 v63, v0
	v_mov_b32_e32 v72, v0
	v_mov_b32_e32 v73, v0
	v_mov_b32_e32 v74, v0
	v_mov_b32_e32 v75, v0
	v_mov_b32_e32 v76, v0
	v_mov_b32_e32 v77, v0
	v_mov_b32_e32 v78, v0
	v_mov_b32_e32 v79, v0
	v_mov_b32_e32 v96, v0
	v_mov_b32_e32 v97, v0
	v_mov_b32_e32 v98, v0
	v_mov_b32_e32 v99, v0
	v_mov_b32_e32 v100, v0
	v_mov_b32_e32 v101, v0
	v_mov_b32_e32 v102, v0
	v_mov_b32_e32 v103, v0
	v_mov_b32_e32 v104, v0
	v_mov_b32_e32 v105, v0
	v_mov_b32_e32 v106, v0
	v_mov_b32_e32 v107, v0
	v_mov_b32_e32 v108, v0
	v_mov_b32_e32 v109, v0
	v_mov_b32_e32 v110, v0
	v_mov_b32_e32 v111, v0
	v_mov_b32_e32 v112, v0
	v_mov_b32_e32 v113, v0
	v_mov_b32_e32 v114, v0
	v_mov_b32_e32 v115, v0
	v_mov_b32_e32 v116, v0
	v_mov_b32_e32 v117, v0
	v_mov_b32_e32 v118, v0
	v_mov_b32_e32 v119, v0
	v_mov_b32_e32 v120, v0
	v_mov_b32_e32 v121, v0
	v_mov_b32_e32 v122, v0
	v_mov_b32_e32 v123, v0
	v_mov_b32_e32 v124, v0
	v_mov_b32_e32 v125, v0
	v_mov_b32_e32 v126, v0
	v_mov_b32_e32 v127, v0
	s_andn2_b64 vcc, exec, s[0:1]
	s_cbranch_vccnz .LBB0_1162
	s_branch .LBB0_1163
